# exposed-latency removal in P2 tail: wconv ticket fetched one ahead (atomic overlapped with item work), conv startup 2 tickets in one atomic, conv loop ticket wait deferred to mid barrier; plus counted
# speedup vs baseline: 1.0052x; 1.0021x over previous
.LBB0_483:
	v_mov_b32_e32 v0, v215
	v_mov_b32_e32 v1, 0
	v_readfirstlane_b32 s3, v0
	v_and_b32_e32 v80, 63, v0
	s_and_b32 s0, s3, 0xc0
	v_or_b32_e32 v81, s0, v80
	v_lshlrev_b32_e32 v0, 3, v81
	s_waitcnt lgkmcnt(0)
	v_lshl_add_u64 v[2:3], s[22:23], 0, v[0:1]
	s_movk_i32 s0, 0x1000
	v_add_co_u32_e32 v4, vcc, s0, v2
	s_movk_i32 s0, 0x2000
	s_nop 0
	v_addc_co_u32_e32 v5, vcc, 0, v3, vcc
	v_add_co_u32_e32 v6, vcc, s0, v2
	s_movk_i32 s0, 0x3000
	s_nop 0
	v_addc_co_u32_e32 v7, vcc, 0, v3, vcc
	v_add_co_u32_e32 v8, vcc, s0, v2
	s_movk_i32 s0, 0x4000
	s_nop 0
	v_addc_co_u32_e32 v9, vcc, 0, v3, vcc
	v_add_co_u32_e32 v10, vcc, s0, v2
	s_movk_i32 s0, 0x5000
	s_nop 0
	v_addc_co_u32_e32 v11, vcc, 0, v3, vcc
	v_add_co_u32_e32 v12, vcc, s0, v2
	s_movk_i32 s0, 0x6000
	s_nop 0
	v_addc_co_u32_e32 v13, vcc, 0, v3, vcc
	v_add_co_u32_e32 v14, vcc, s0, v2
	s_movk_i32 s0, 0x7000
	s_nop 0
	v_addc_co_u32_e32 v15, vcc, 0, v3, vcc
	global_load_dwordx2 v[16:17], v[6:7], off
	global_load_dwordx2 v[18:19], v[6:7], off offset:2048
	global_load_dwordx2 v[20:21], v[10:11], off offset:-4096
	global_load_dwordx2 v[22:23], v[10:11], off
	global_load_dwordx2 v[24:25], v[10:11], off offset:2048
	global_load_dwordx2 v[26:27], v[14:15], off offset:-4096
	global_load_dwordx2 v[28:29], v[14:15], off
	global_load_dwordx2 v[30:31], v[14:15], off offset:2048
	v_add_co_u32_e32 v10, vcc, s0, v2
	s_mov_b32 s0, 0x8000
	s_nop 0
	v_addc_co_u32_e32 v11, vcc, 0, v3, vcc
	v_add_co_u32_e32 v14, vcc, s0, v2
	s_mov_b32 s0, 0x9000
	s_nop 0
	v_addc_co_u32_e32 v15, vcc, 0, v3, vcc
	global_load_dwordx2 v[32:33], v[4:5], off offset:2048
	global_load_dwordx2 v[34:35], v[8:9], off offset:2048
	global_load_dwordx2 v[36:37], v[12:13], off offset:2048
	global_load_dwordx2 v[38:39], v[10:11], off offset:2048
	v_add_co_u32_e32 v4, vcc, s0, v2
	s_mov_b32 s0, 0xa000
	s_nop 0
	v_addc_co_u32_e32 v5, vcc, 0, v3, vcc
	v_add_co_u32_e32 v8, vcc, s0, v2
	s_mov_b32 s0, 0xb000
	s_nop 0
	v_addc_co_u32_e32 v9, vcc, 0, v3, vcc
	v_add_co_u32_e32 v10, vcc, s0, v2
	s_mov_b32 s0, 0xc000
	s_nop 0
	v_addc_co_u32_e32 v11, vcc, 0, v3, vcc
	v_add_co_u32_e32 v12, vcc, s0, v2
	s_mov_b32 s0, 0xd000
	s_nop 0
	v_addc_co_u32_e32 v13, vcc, 0, v3, vcc
	global_load_dwordx2 v[40:41], v[14:15], off offset:-4096
	global_load_dwordx2 v[42:43], v[14:15], off
	global_load_dwordx2 v[44:45], v[14:15], off offset:2048
	global_load_dwordx2 v[46:47], v[8:9], off offset:-4096
	global_load_dwordx2 v[48:49], v[8:9], off
	global_load_dwordx2 v[50:51], v[8:9], off offset:2048
	global_load_dwordx2 v[52:53], v[12:13], off offset:-4096
	global_load_dwordx2 v[54:55], v[12:13], off
	v_add_co_u32_e32 v8, vcc, s0, v2
	s_mov_b32 s0, 0xe000
	s_nop 0
	v_addc_co_u32_e32 v9, vcc, 0, v3, vcc
	v_add_co_u32_e32 v14, vcc, s0, v2
	v_lshlrev_b32_e32 v82, 5, v80
	s_nop 0
	v_addc_co_u32_e32 v15, vcc, 0, v3, vcc
	v_add_co_u32_e32 v2, vcc, 0xf000, v2
	global_load_dwordx2 v[56:57], v[12:13], off offset:2048
	global_load_dwordx2 v[58:59], v[14:15], off offset:-4096
	global_load_dwordx2 v[60:61], v[14:15], off
	global_load_dwordx2 v[62:63], v[14:15], off offset:2048
	v_addc_co_u32_e32 v3, vcc, 0, v3, vcc
	global_load_dwordx2 v[64:65], v[4:5], off offset:2048
	global_load_dwordx2 v[66:67], v[10:11], off offset:2048
	global_load_dwordx2 v[68:69], v[8:9], off offset:2048
	global_load_dwordx2 v[70:71], v[2:3], off
	global_load_dwordx2 v[72:73], v0, s[22:23]
	global_load_dwordx2 v[74:75], v0, s[22:23] offset:2048
	global_load_dwordx2 v[76:77], v[6:7], off offset:-4096
	global_load_dwordx2 v[78:79], v0, s[24:25]
	s_nop 0
	global_load_dwordx4 v[0:3], v82, s[26:27] offset:16
	global_load_dwordx4 v[4:7], v82, s[28:29] offset:16
	global_load_dwordx4 v[8:11], v82, s[26:27]
	global_load_dwordx4 v[12:15], v82, s[28:29]
	s_ashr_i32 s10, s3, 6
	v_lshlrev_b32_e32 v84, 3, v80
	v_or_b32_e32 v80, s10, v80
	v_lshlrev_b32_e32 v101, 1, v81
	v_cmp_eq_u32_e64 s[4:5], 0, v80
	s_and_saveexec_b64 s[0:1], s[4:5]
	v_readlane_b32 s68, v254, 0
	v_readlane_b32 s76, v254, 19
	v_readlane_b32 s69, v254, 1
	v_readlane_b32 s70, v254, 2
	v_readlane_b32 s71, v254, 3
	v_readlane_b32 s72, v254, 4
	v_readlane_b32 s73, v254, 5
	v_readlane_b32 s74, v254, 6
	v_readlane_b32 s75, v254, 7
	v_readlane_b32 s77, v254, 20
	s_cbranch_execz .LBB0_489
	s_mov_b64 s[8:9], exec
	v_mbcnt_lo_u32_b32 v80, s8, 0
	v_mbcnt_hi_u32_b32 v80, s9, v80
	v_cmp_eq_u32_e32 vcc, 0, v80
	s_and_saveexec_b64 s[6:7], vcc
	s_cbranch_execz .LBB0_486
	v_mov_b32_e32 v81, 0
	v_mov_b32_e32 v82, 2
	global_atomic_add v81, v81, v82, s[62:63] offset:128 sc0
.LBB0_486:
	s_or_b64 exec, exec, s[6:7]
	s_waitcnt vmcnt(0)
	v_readfirstlane_b32 s2, v81
	s_nop 1
	v_add_u32_e32 v80, s2, v80
	s_add_i32 s2, 0, 0x23f40
	v_mov_b32_e32 v81, s2
	ds_write_b32 v81, v80
	v_add_u32_e32 v80, 1, v80
	ds_write_b32 v81, v80 offset:4

.LBB0_491:
	s_waitcnt vmcnt(45)
	v_lshlrev_b32_e32 v180, 16, v179
	v_and_b32_e32 v181, 0xffff0000, v179
	v_pk_fma_f32 v[180:181], v[72:73], v[180:181], v[78:79]
	s_waitcnt vmcnt(44)
	v_lshlrev_b32_e32 v182, 16, v178
	v_and_b32_e32 v183, 0xffff0000, v178
	v_pk_fma_f32 v[178:179], v[74:75], v[182:183], v[180:181]
	v_pk_fma_f32 v[180:181], v[72:73], v[182:183], v[78:79]
	s_waitcnt vmcnt(43)
	v_lshlrev_b32_e32 v182, 16, v177
	v_and_b32_e32 v183, 0xffff0000, v177
	v_pk_fma_f32 v[178:179], v[76:77], v[182:183], v[178:179]
	v_pk_fma_f32 v[180:181], v[74:75], v[182:183], v[180:181]
	v_pk_fma_f32 v[182:183], v[72:73], v[182:183], v[78:79]
	s_waitcnt vmcnt(42)
	v_lshlrev_b32_e32 v184, 16, v176
	v_and_b32_e32 v185, 0xffff0000, v176
	v_pk_fma_f32 v[176:177], v[32:33], v[184:185], v[178:179]
	v_pk_fma_f32 v[178:179], v[76:77], v[184:185], v[180:181]
	v_pk_fma_f32 v[180:181], v[74:75], v[184:185], v[182:183]
	v_pk_fma_f32 v[182:183], v[72:73], v[184:185], v[78:79]
	s_waitcnt vmcnt(41)
	v_lshlrev_b32_e32 v184, 16, v175
	v_and_b32_e32 v185, 0xffff0000, v175
	v_pk_fma_f32 v[176:177], v[16:17], v[184:185], v[176:177]
	v_pk_fma_f32 v[178:179], v[32:33], v[184:185], v[178:179]
	v_pk_fma_f32 v[180:181], v[76:77], v[184:185], v[180:181]
	v_pk_fma_f32 v[182:183], v[74:75], v[184:185], v[182:183]
	v_pk_fma_f32 v[184:185], v[72:73], v[184:185], v[78:79]
	s_waitcnt vmcnt(40)
	v_lshlrev_b32_e32 v186, 16, v174
	v_and_b32_e32 v187, 0xffff0000, v174
	v_pk_fma_f32 v[174:175], v[18:19], v[186:187], v[176:177]
	v_pk_fma_f32 v[176:177], v[16:17], v[186:187], v[178:179]
	v_pk_fma_f32 v[178:179], v[32:33], v[186:187], v[180:181]
	v_pk_fma_f32 v[180:181], v[76:77], v[186:187], v[182:183]
	v_pk_fma_f32 v[182:183], v[74:75], v[186:187], v[184:185]
	v_pk_fma_f32 v[184:185], v[72:73], v[186:187], v[78:79]
	s_waitcnt vmcnt(39)
	v_lshlrev_b32_e32 v186, 16, v173
	v_and_b32_e32 v187, 0xffff0000, v173
	v_pk_fma_f32 v[174:175], v[20:21], v[186:187], v[174:175]
	v_pk_fma_f32 v[176:177], v[18:19], v[186:187], v[176:177]
	v_pk_fma_f32 v[178:179], v[16:17], v[186:187], v[178:179]
	v_pk_fma_f32 v[180:181], v[32:33], v[186:187], v[180:181]
	v_pk_fma_f32 v[182:183], v[76:77], v[186:187], v[182:183]
	v_pk_fma_f32 v[184:185], v[74:75], v[186:187], v[184:185]
	v_pk_fma_f32 v[186:187], v[72:73], v[186:187], v[78:79]
	s_waitcnt vmcnt(38)
	v_lshlrev_b32_e32 v188, 16, v171
	v_and_b32_e32 v189, 0xffff0000, v171
	v_pk_fma_f32 v[174:175], v[34:35], v[188:189], v[174:175]
	v_pk_fma_f32 v[176:177], v[20:21], v[188:189], v[176:177]
	v_pk_fma_f32 v[178:179], v[18:19], v[188:189], v[178:179]
	v_pk_fma_f32 v[180:181], v[16:17], v[188:189], v[180:181]
	v_pk_fma_f32 v[182:183], v[32:33], v[188:189], v[182:183]
	v_pk_fma_f32 v[184:185], v[76:77], v[188:189], v[184:185]
	v_pk_fma_f32 v[186:187], v[74:75], v[188:189], v[186:187]
	v_pk_fma_f32 v[188:189], v[72:73], v[188:189], v[78:79]
	s_waitcnt vmcnt(37)
	v_lshlrev_b32_e32 v190, 16, v172
	v_and_b32_e32 v191, 0xffff0000, v172
	v_pk_fma_f32 v[172:173], v[22:23], v[190:191], v[174:175]
	v_pk_fma_f32 v[174:175], v[34:35], v[190:191], v[176:177]
	v_pk_fma_f32 v[176:177], v[20:21], v[190:191], v[178:179]
	v_pk_fma_f32 v[178:179], v[18:19], v[190:191], v[180:181]
	v_pk_fma_f32 v[180:181], v[16:17], v[190:191], v[182:183]
	v_pk_fma_f32 v[182:183], v[32:33], v[190:191], v[184:185]
	v_pk_fma_f32 v[184:185], v[76:77], v[190:191], v[186:187]
	v_pk_fma_f32 v[186:187], v[74:75], v[190:191], v[188:189]
	v_pk_fma_f32 v[188:189], v[72:73], v[190:191], v[78:79]
	s_waitcnt vmcnt(36)
	v_lshlrev_b32_e32 v190, 16, v170
	v_and_b32_e32 v191, 0xffff0000, v170
	v_pk_fma_f32 v[170:171], v[24:25], v[190:191], v[172:173]
	v_pk_fma_f32 v[172:173], v[22:23], v[190:191], v[174:175]
	v_pk_fma_f32 v[174:175], v[34:35], v[190:191], v[176:177]
	v_pk_fma_f32 v[176:177], v[20:21], v[190:191], v[178:179]
	v_pk_fma_f32 v[178:179], v[18:19], v[190:191], v[180:181]
	v_pk_fma_f32 v[180:181], v[16:17], v[190:191], v[182:183]
	v_pk_fma_f32 v[182:183], v[32:33], v[190:191], v[184:185]
	v_pk_fma_f32 v[184:185], v[76:77], v[190:191], v[186:187]
	v_pk_fma_f32 v[186:187], v[74:75], v[190:191], v[188:189]
	v_pk_fma_f32 v[188:189], v[72:73], v[190:191], v[78:79]
	s_waitcnt vmcnt(35)
	v_lshlrev_b32_e32 v190, 16, v169
	v_and_b32_e32 v191, 0xffff0000, v169
	v_pk_fma_f32 v[170:171], v[26:27], v[190:191], v[170:171]
	v_pk_fma_f32 v[172:173], v[24:25], v[190:191], v[172:173]
	v_pk_fma_f32 v[174:175], v[22:23], v[190:191], v[174:175]
	v_pk_fma_f32 v[176:177], v[34:35], v[190:191], v[176:177]
	v_pk_fma_f32 v[178:179], v[20:21], v[190:191], v[178:179]
	v_pk_fma_f32 v[180:181], v[18:19], v[190:191], v[180:181]
	v_pk_fma_f32 v[182:183], v[16:17], v[190:191], v[182:183]
	v_pk_fma_f32 v[184:185], v[32:33], v[190:191], v[184:185]
	v_pk_fma_f32 v[186:187], v[76:77], v[190:191], v[186:187]
	v_pk_fma_f32 v[188:189], v[74:75], v[190:191], v[188:189]
	v_pk_fma_f32 v[190:191], v[72:73], v[190:191], v[78:79]
	s_waitcnt vmcnt(34)
	v_lshlrev_b32_e32 v192, 16, v168
	v_and_b32_e32 v193, 0xffff0000, v168
	v_pk_fma_f32 v[168:169], v[36:37], v[192:193], v[170:171]
	v_pk_fma_f32 v[170:171], v[26:27], v[192:193], v[172:173]
	v_pk_fma_f32 v[172:173], v[24:25], v[192:193], v[174:175]
	v_pk_fma_f32 v[174:175], v[22:23], v[192:193], v[176:177]
	v_pk_fma_f32 v[176:177], v[34:35], v[192:193], v[178:179]
	v_pk_fma_f32 v[178:179], v[20:21], v[192:193], v[180:181]
	v_pk_fma_f32 v[180:181], v[18:19], v[192:193], v[182:183]
	v_pk_fma_f32 v[182:183], v[16:17], v[192:193], v[184:185]
	v_pk_fma_f32 v[184:185], v[32:33], v[192:193], v[186:187]
	v_pk_fma_f32 v[186:187], v[76:77], v[192:193], v[188:189]
	v_pk_fma_f32 v[188:189], v[74:75], v[192:193], v[190:191]
	v_pk_fma_f32 v[190:191], v[72:73], v[192:193], v[78:79]
	s_waitcnt vmcnt(33)
	v_lshlrev_b32_e32 v192, 16, v167
	v_and_b32_e32 v193, 0xffff0000, v167
	v_pk_fma_f32 v[168:169], v[28:29], v[192:193], v[168:169]
	v_pk_fma_f32 v[170:171], v[36:37], v[192:193], v[170:171]
	v_pk_fma_f32 v[172:173], v[26:27], v[192:193], v[172:173]
	v_pk_fma_f32 v[174:175], v[24:25], v[192:193], v[174:175]
	v_pk_fma_f32 v[176:177], v[22:23], v[192:193], v[176:177]
	v_pk_fma_f32 v[178:179], v[34:35], v[192:193], v[178:179]
	v_pk_fma_f32 v[180:181], v[20:21], v[192:193], v[180:181]
	v_pk_fma_f32 v[182:183], v[18:19], v[192:193], v[182:183]
	v_pk_fma_f32 v[184:185], v[16:17], v[192:193], v[184:185]
	v_pk_fma_f32 v[186:187], v[32:33], v[192:193], v[186:187]
	v_pk_fma_f32 v[188:189], v[76:77], v[192:193], v[188:189]
	v_pk_fma_f32 v[190:191], v[74:75], v[192:193], v[190:191]
	v_pk_fma_f32 v[192:193], v[72:73], v[192:193], v[78:79]
	s_waitcnt vmcnt(32)
	v_lshlrev_b32_e32 v194, 16, v166
	v_and_b32_e32 v195, 0xffff0000, v166
	v_pk_fma_f32 v[166:167], v[30:31], v[194:195], v[168:169]
	v_pk_fma_f32 v[168:169], v[28:29], v[194:195], v[170:171]
	v_pk_fma_f32 v[170:171], v[36:37], v[194:195], v[172:173]
	v_pk_fma_f32 v[172:173], v[26:27], v[194:195], v[174:175]
	v_pk_fma_f32 v[174:175], v[24:25], v[194:195], v[176:177]
	v_pk_fma_f32 v[176:177], v[22:23], v[194:195], v[178:179]
	v_pk_fma_f32 v[178:179], v[34:35], v[194:195], v[180:181]
	v_pk_fma_f32 v[180:181], v[20:21], v[194:195], v[182:183]
	v_pk_fma_f32 v[182:183], v[18:19], v[194:195], v[184:185]
	v_pk_fma_f32 v[184:185], v[16:17], v[194:195], v[186:187]
	v_pk_fma_f32 v[186:187], v[32:33], v[194:195], v[188:189]
	v_pk_fma_f32 v[188:189], v[76:77], v[194:195], v[190:191]
	v_pk_fma_f32 v[190:191], v[74:75], v[194:195], v[192:193]
	v_pk_fma_f32 v[192:193], v[72:73], v[194:195], v[78:79]
	s_waitcnt vmcnt(31)
	v_lshlrev_b32_e32 v194, 16, v165
	v_and_b32_e32 v195, 0xffff0000, v165
	v_pk_fma_f32 v[166:167], v[40:41], v[194:195], v[166:167]
	v_pk_fma_f32 v[168:169], v[30:31], v[194:195], v[168:169]
	v_pk_fma_f32 v[170:171], v[28:29], v[194:195], v[170:171]
	v_pk_fma_f32 v[172:173], v[36:37], v[194:195], v[172:173]
	v_pk_fma_f32 v[174:175], v[26:27], v[194:195], v[174:175]
	v_pk_fma_f32 v[176:177], v[24:25], v[194:195], v[176:177]
	v_pk_fma_f32 v[178:179], v[22:23], v[194:195], v[178:179]
	v_pk_fma_f32 v[180:181], v[34:35], v[194:195], v[180:181]
	v_pk_fma_f32 v[182:183], v[20:21], v[194:195], v[182:183]
	v_pk_fma_f32 v[184:185], v[18:19], v[194:195], v[184:185]
	v_pk_fma_f32 v[186:187], v[16:17], v[194:195], v[186:187]
	v_pk_fma_f32 v[188:189], v[32:33], v[194:195], v[188:189]
	v_pk_fma_f32 v[190:191], v[76:77], v[194:195], v[190:191]
	v_pk_fma_f32 v[192:193], v[74:75], v[194:195], v[192:193]
	v_pk_fma_f32 v[194:195], v[72:73], v[194:195], v[78:79]
	s_waitcnt vmcnt(30)
	v_lshlrev_b32_e32 v196, 16, v164
	v_and_b32_e32 v197, 0xffff0000, v164
	v_pk_fma_f32 v[164:165], v[38:39], v[196:197], v[166:167]
	v_pk_fma_f32 v[166:167], v[40:41], v[196:197], v[168:169]
	v_pk_fma_f32 v[168:169], v[30:31], v[196:197], v[170:171]
	v_pk_fma_f32 v[170:171], v[28:29], v[196:197], v[172:173]
	v_pk_fma_f32 v[172:173], v[36:37], v[196:197], v[174:175]
	v_pk_fma_f32 v[174:175], v[26:27], v[196:197], v[176:177]
	v_pk_fma_f32 v[176:177], v[24:25], v[196:197], v[178:179]
	v_pk_fma_f32 v[178:179], v[22:23], v[196:197], v[180:181]
	v_pk_fma_f32 v[180:181], v[34:35], v[196:197], v[182:183]
	v_pk_fma_f32 v[182:183], v[20:21], v[196:197], v[184:185]
	v_pk_fma_f32 v[184:185], v[18:19], v[196:197], v[186:187]
	v_pk_fma_f32 v[186:187], v[16:17], v[196:197], v[188:189]
	v_pk_fma_f32 v[188:189], v[32:33], v[196:197], v[190:191]
	v_pk_fma_f32 v[190:191], v[76:77], v[196:197], v[192:193]
	v_pk_fma_f32 v[192:193], v[74:75], v[196:197], v[194:195]
	v_pk_fma_f32 v[194:195], v[72:73], v[196:197], v[78:79]
	s_waitcnt vmcnt(29)
	v_lshlrev_b32_e32 v196, 16, v163
	v_and_b32_e32 v197, 0xffff0000, v163
	v_pk_fma_f32 v[164:165], v[42:43], v[196:197], v[164:165]
	v_pk_fma_f32 v[166:167], v[38:39], v[196:197], v[166:167]
	v_pk_fma_f32 v[168:169], v[40:41], v[196:197], v[168:169]
	v_pk_fma_f32 v[170:171], v[30:31], v[196:197], v[170:171]
	v_pk_fma_f32 v[172:173], v[28:29], v[196:197], v[172:173]
	v_pk_fma_f32 v[174:175], v[36:37], v[196:197], v[174:175]
	v_pk_fma_f32 v[176:177], v[26:27], v[196:197], v[176:177]
	v_pk_fma_f32 v[178:179], v[24:25], v[196:197], v[178:179]
	v_pk_fma_f32 v[180:181], v[22:23], v[196:197], v[180:181]
	v_pk_fma_f32 v[182:183], v[34:35], v[196:197], v[182:183]
	v_pk_fma_f32 v[184:185], v[20:21], v[196:197], v[184:185]
	v_pk_fma_f32 v[186:187], v[18:19], v[196:197], v[186:187]
	v_pk_fma_f32 v[188:189], v[16:17], v[196:197], v[188:189]
	v_pk_fma_f32 v[190:191], v[32:33], v[196:197], v[190:191]
	v_pk_fma_f32 v[192:193], v[76:77], v[196:197], v[192:193]
	v_pk_fma_f32 v[194:195], v[74:75], v[196:197], v[194:195]
	s_waitcnt vmcnt(28)
	v_lshlrev_b32_e32 v196, 16, v162
	v_and_b32_e32 v197, 0xffff0000, v162
	v_pk_fma_f32 v[162:163], v[44:45], v[196:197], v[164:165]
	v_pk_fma_f32 v[164:165], v[42:43], v[196:197], v[166:167]
	v_pk_fma_f32 v[166:167], v[38:39], v[196:197], v[168:169]
	v_pk_fma_f32 v[168:169], v[40:41], v[196:197], v[170:171]
	v_pk_fma_f32 v[170:171], v[30:31], v[196:197], v[172:173]
	v_pk_fma_f32 v[172:173], v[28:29], v[196:197], v[174:175]
	v_pk_fma_f32 v[174:175], v[36:37], v[196:197], v[176:177]
	v_pk_fma_f32 v[176:177], v[26:27], v[196:197], v[178:179]
	v_pk_fma_f32 v[178:179], v[24:25], v[196:197], v[180:181]
	v_pk_fma_f32 v[180:181], v[22:23], v[196:197], v[182:183]
	v_pk_fma_f32 v[182:183], v[34:35], v[196:197], v[184:185]
	v_pk_fma_f32 v[184:185], v[20:21], v[196:197], v[186:187]
	v_pk_fma_f32 v[186:187], v[18:19], v[196:197], v[188:189]
	v_pk_fma_f32 v[188:189], v[16:17], v[196:197], v[190:191]
	v_pk_fma_f32 v[190:191], v[32:33], v[196:197], v[192:193]
	v_pk_fma_f32 v[192:193], v[76:77], v[196:197], v[194:195]
	s_waitcnt vmcnt(27)
	v_lshlrev_b32_e32 v194, 16, v161
	v_and_b32_e32 v195, 0xffff0000, v161
	v_pk_fma_f32 v[162:163], v[46:47], v[194:195], v[162:163]
	v_pk_fma_f32 v[164:165], v[44:45], v[194:195], v[164:165]
	v_pk_fma_f32 v[166:167], v[42:43], v[194:195], v[166:167]
	v_pk_fma_f32 v[168:169], v[38:39], v[194:195], v[168:169]
	v_pk_fma_f32 v[170:171], v[40:41], v[194:195], v[170:171]
	v_pk_fma_f32 v[172:173], v[30:31], v[194:195], v[172:173]
	v_pk_fma_f32 v[174:175], v[28:29], v[194:195], v[174:175]
	v_pk_fma_f32 v[176:177], v[36:37], v[194:195], v[176:177]
	v_pk_fma_f32 v[178:179], v[26:27], v[194:195], v[178:179]
	v_pk_fma_f32 v[180:181], v[24:25], v[194:195], v[180:181]
	v_pk_fma_f32 v[182:183], v[22:23], v[194:195], v[182:183]
	v_pk_fma_f32 v[184:185], v[34:35], v[194:195], v[184:185]
	v_pk_fma_f32 v[186:187], v[20:21], v[194:195], v[186:187]
	v_pk_fma_f32 v[188:189], v[18:19], v[194:195], v[188:189]
	v_pk_fma_f32 v[190:191], v[16:17], v[194:195], v[190:191]
	v_pk_fma_f32 v[192:193], v[32:33], v[194:195], v[192:193]
	s_waitcnt vmcnt(26)
	v_lshlrev_b32_e32 v194, 16, v160
	v_and_b32_e32 v195, 0xffff0000, v160
	v_pk_fma_f32 v[160:161], v[64:65], v[194:195], v[162:163]
	v_pk_fma_f32 v[162:163], v[46:47], v[194:195], v[164:165]
	v_pk_fma_f32 v[164:165], v[44:45], v[194:195], v[166:167]
	v_pk_fma_f32 v[166:167], v[42:43], v[194:195], v[168:169]
	v_pk_fma_f32 v[168:169], v[38:39], v[194:195], v[170:171]
	v_pk_fma_f32 v[170:171], v[40:41], v[194:195], v[172:173]
	v_pk_fma_f32 v[172:173], v[30:31], v[194:195], v[174:175]
	v_pk_fma_f32 v[174:175], v[28:29], v[194:195], v[176:177]
	v_pk_fma_f32 v[176:177], v[36:37], v[194:195], v[178:179]
	v_pk_fma_f32 v[178:179], v[26:27], v[194:195], v[180:181]
	v_pk_fma_f32 v[180:181], v[24:25], v[194:195], v[182:183]
	v_pk_fma_f32 v[182:183], v[22:23], v[194:195], v[184:185]
	v_pk_fma_f32 v[184:185], v[34:35], v[194:195], v[186:187]
	v_pk_fma_f32 v[186:187], v[20:21], v[194:195], v[188:189]
	v_pk_fma_f32 v[188:189], v[18:19], v[194:195], v[190:191]
	v_pk_fma_f32 v[190:191], v[16:17], v[194:195], v[192:193]
	s_waitcnt vmcnt(25)
	v_lshlrev_b32_e32 v192, 16, v159
	v_and_b32_e32 v193, 0xffff0000, v159
	v_pk_fma_f32 v[160:161], v[48:49], v[192:193], v[160:161]
	v_pk_fma_f32 v[162:163], v[64:65], v[192:193], v[162:163]
	v_pk_fma_f32 v[164:165], v[46:47], v[192:193], v[164:165]
	v_pk_fma_f32 v[166:167], v[44:45], v[192:193], v[166:167]
	v_pk_fma_f32 v[168:169], v[42:43], v[192:193], v[168:169]
	v_pk_fma_f32 v[170:171], v[38:39], v[192:193], v[170:171]
	v_pk_fma_f32 v[172:173], v[40:41], v[192:193], v[172:173]
	v_pk_fma_f32 v[174:175], v[30:31], v[192:193], v[174:175]
	v_pk_fma_f32 v[176:177], v[28:29], v[192:193], v[176:177]
	v_pk_fma_f32 v[178:179], v[36:37], v[192:193], v[178:179]
	v_pk_fma_f32 v[180:181], v[26:27], v[192:193], v[180:181]
	v_pk_fma_f32 v[182:183], v[24:25], v[192:193], v[182:183]
	v_pk_fma_f32 v[184:185], v[22:23], v[192:193], v[184:185]
	v_pk_fma_f32 v[186:187], v[34:35], v[192:193], v[186:187]
	v_pk_fma_f32 v[188:189], v[20:21], v[192:193], v[188:189]
	v_pk_fma_f32 v[190:191], v[18:19], v[192:193], v[190:191]
	s_waitcnt vmcnt(24)
	v_lshlrev_b32_e32 v192, 16, v158
	v_and_b32_e32 v193, 0xffff0000, v158
	v_pk_fma_f32 v[158:159], v[50:51], v[192:193], v[160:161]
	v_pk_fma_f32 v[160:161], v[48:49], v[192:193], v[162:163]
	v_pk_fma_f32 v[162:163], v[64:65], v[192:193], v[164:165]
	v_pk_fma_f32 v[164:165], v[46:47], v[192:193], v[166:167]
	v_pk_fma_f32 v[166:167], v[44:45], v[192:193], v[168:169]
	v_pk_fma_f32 v[168:169], v[42:43], v[192:193], v[170:171]
	v_pk_fma_f32 v[170:171], v[38:39], v[192:193], v[172:173]
	v_pk_fma_f32 v[172:173], v[40:41], v[192:193], v[174:175]
	v_pk_fma_f32 v[174:175], v[30:31], v[192:193], v[176:177]
	v_pk_fma_f32 v[176:177], v[28:29], v[192:193], v[178:179]
	v_pk_fma_f32 v[178:179], v[36:37], v[192:193], v[180:181]
	v_pk_fma_f32 v[180:181], v[26:27], v[192:193], v[182:183]
	v_pk_fma_f32 v[182:183], v[24:25], v[192:193], v[184:185]
	v_pk_fma_f32 v[184:185], v[22:23], v[192:193], v[186:187]
	v_pk_fma_f32 v[186:187], v[34:35], v[192:193], v[188:189]
	v_pk_fma_f32 v[188:189], v[20:21], v[192:193], v[190:191]
	s_waitcnt vmcnt(23)
	v_lshlrev_b32_e32 v190, 16, v157
	v_and_b32_e32 v191, 0xffff0000, v157
	v_pk_fma_f32 v[158:159], v[52:53], v[190:191], v[158:159]
	v_pk_fma_f32 v[160:161], v[50:51], v[190:191], v[160:161]
	v_pk_fma_f32 v[162:163], v[48:49], v[190:191], v[162:163]
	v_pk_fma_f32 v[164:165], v[64:65], v[190:191], v[164:165]
	v_pk_fma_f32 v[166:167], v[46:47], v[190:191], v[166:167]
	v_pk_fma_f32 v[168:169], v[44:45], v[190:191], v[168:169]
	v_pk_fma_f32 v[170:171], v[42:43], v[190:191], v[170:171]
	v_pk_fma_f32 v[172:173], v[38:39], v[190:191], v[172:173]
	v_pk_fma_f32 v[174:175], v[40:41], v[190:191], v[174:175]
	v_pk_fma_f32 v[176:177], v[30:31], v[190:191], v[176:177]
	v_pk_fma_f32 v[178:179], v[28:29], v[190:191], v[178:179]
	v_pk_fma_f32 v[180:181], v[36:37], v[190:191], v[180:181]
	v_pk_fma_f32 v[182:183], v[26:27], v[190:191], v[182:183]
	v_pk_fma_f32 v[184:185], v[24:25], v[190:191], v[184:185]
	v_pk_fma_f32 v[186:187], v[22:23], v[190:191], v[186:187]
	v_pk_fma_f32 v[188:189], v[34:35], v[190:191], v[188:189]
	s_waitcnt vmcnt(22)
	v_lshlrev_b32_e32 v190, 16, v156
	v_and_b32_e32 v191, 0xffff0000, v156
	v_pk_fma_f32 v[156:157], v[66:67], v[190:191], v[158:159]
	v_pk_fma_f32 v[158:159], v[52:53], v[190:191], v[160:161]
	v_pk_fma_f32 v[160:161], v[50:51], v[190:191], v[162:163]
	v_pk_fma_f32 v[162:163], v[48:49], v[190:191], v[164:165]
	v_pk_fma_f32 v[164:165], v[64:65], v[190:191], v[166:167]
	v_pk_fma_f32 v[166:167], v[46:47], v[190:191], v[168:169]
	v_pk_fma_f32 v[168:169], v[44:45], v[190:191], v[170:171]
	v_pk_fma_f32 v[170:171], v[42:43], v[190:191], v[172:173]
	v_pk_fma_f32 v[172:173], v[38:39], v[190:191], v[174:175]
	v_pk_fma_f32 v[174:175], v[40:41], v[190:191], v[176:177]
	v_pk_fma_f32 v[176:177], v[30:31], v[190:191], v[178:179]
	v_pk_fma_f32 v[178:179], v[28:29], v[190:191], v[180:181]
	v_pk_fma_f32 v[180:181], v[36:37], v[190:191], v[182:183]
	v_pk_fma_f32 v[182:183], v[26:27], v[190:191], v[184:185]
	v_pk_fma_f32 v[184:185], v[24:25], v[190:191], v[186:187]
	v_pk_fma_f32 v[186:187], v[22:23], v[190:191], v[188:189]
	s_waitcnt vmcnt(21)
	v_lshlrev_b32_e32 v188, 16, v155
	v_and_b32_e32 v189, 0xffff0000, v155
	v_pk_fma_f32 v[156:157], v[54:55], v[188:189], v[156:157]
	v_pk_fma_f32 v[158:159], v[66:67], v[188:189], v[158:159]
	v_pk_fma_f32 v[160:161], v[52:53], v[188:189], v[160:161]
	v_pk_fma_f32 v[162:163], v[50:51], v[188:189], v[162:163]
	v_pk_fma_f32 v[164:165], v[48:49], v[188:189], v[164:165]
	v_pk_fma_f32 v[166:167], v[64:65], v[188:189], v[166:167]
	v_pk_fma_f32 v[168:169], v[46:47], v[188:189], v[168:169]
	v_pk_fma_f32 v[170:171], v[44:45], v[188:189], v[170:171]
	v_pk_fma_f32 v[172:173], v[42:43], v[188:189], v[172:173]
	v_pk_fma_f32 v[174:175], v[38:39], v[188:189], v[174:175]
	v_pk_fma_f32 v[176:177], v[40:41], v[188:189], v[176:177]
	v_pk_fma_f32 v[178:179], v[30:31], v[188:189], v[178:179]
	v_pk_fma_f32 v[180:181], v[28:29], v[188:189], v[180:181]
	v_pk_fma_f32 v[182:183], v[36:37], v[188:189], v[182:183]
	v_pk_fma_f32 v[184:185], v[26:27], v[188:189], v[184:185]
	v_pk_fma_f32 v[186:187], v[24:25], v[188:189], v[186:187]
	s_waitcnt vmcnt(20)
	v_lshlrev_b32_e32 v188, 16, v154
	v_and_b32_e32 v189, 0xffff0000, v154
	v_pk_fma_f32 v[154:155], v[56:57], v[188:189], v[156:157]
	v_pk_fma_f32 v[156:157], v[54:55], v[188:189], v[158:159]
	v_pk_fma_f32 v[158:159], v[66:67], v[188:189], v[160:161]
	v_pk_fma_f32 v[160:161], v[52:53], v[188:189], v[162:163]
	v_pk_fma_f32 v[162:163], v[50:51], v[188:189], v[164:165]
	v_pk_fma_f32 v[164:165], v[48:49], v[188:189], v[166:167]
	v_pk_fma_f32 v[166:167], v[64:65], v[188:189], v[168:169]
	v_pk_fma_f32 v[168:169], v[46:47], v[188:189], v[170:171]
	v_pk_fma_f32 v[170:171], v[44:45], v[188:189], v[172:173]
	v_pk_fma_f32 v[172:173], v[42:43], v[188:189], v[174:175]
	v_pk_fma_f32 v[174:175], v[38:39], v[188:189], v[176:177]
	v_pk_fma_f32 v[176:177], v[40:41], v[188:189], v[178:179]
	v_pk_fma_f32 v[178:179], v[30:31], v[188:189], v[180:181]
	v_pk_fma_f32 v[180:181], v[28:29], v[188:189], v[182:183]
	v_pk_fma_f32 v[182:183], v[36:37], v[188:189], v[184:185]
	v_pk_fma_f32 v[184:185], v[26:27], v[188:189], v[186:187]
	s_waitcnt vmcnt(19)
	v_lshlrev_b32_e32 v186, 16, v153
	v_and_b32_e32 v187, 0xffff0000, v153
	v_pk_fma_f32 v[154:155], v[58:59], v[186:187], v[154:155]
	v_pk_fma_f32 v[156:157], v[56:57], v[186:187], v[156:157]
	v_pk_fma_f32 v[158:159], v[54:55], v[186:187], v[158:159]
	v_pk_fma_f32 v[160:161], v[66:67], v[186:187], v[160:161]
	v_pk_fma_f32 v[162:163], v[52:53], v[186:187], v[162:163]
	v_pk_fma_f32 v[164:165], v[50:51], v[186:187], v[164:165]
	v_pk_fma_f32 v[166:167], v[48:49], v[186:187], v[166:167]
	v_pk_fma_f32 v[168:169], v[64:65], v[186:187], v[168:169]
	v_pk_fma_f32 v[170:171], v[46:47], v[186:187], v[170:171]
	v_pk_fma_f32 v[172:173], v[44:45], v[186:187], v[172:173]
	v_pk_fma_f32 v[174:175], v[42:43], v[186:187], v[174:175]
	v_pk_fma_f32 v[176:177], v[38:39], v[186:187], v[176:177]
	v_pk_fma_f32 v[178:179], v[40:41], v[186:187], v[178:179]
	v_pk_fma_f32 v[180:181], v[30:31], v[186:187], v[180:181]
	v_pk_fma_f32 v[182:183], v[28:29], v[186:187], v[182:183]
	v_pk_fma_f32 v[184:185], v[36:37], v[186:187], v[184:185]
	s_waitcnt vmcnt(18)
	v_lshlrev_b32_e32 v186, 16, v152
	v_and_b32_e32 v187, 0xffff0000, v152
	v_pk_fma_f32 v[152:153], v[68:69], v[186:187], v[154:155]
	v_pk_fma_f32 v[154:155], v[58:59], v[186:187], v[156:157]
	v_pk_fma_f32 v[156:157], v[56:57], v[186:187], v[158:159]
	v_pk_fma_f32 v[158:159], v[54:55], v[186:187], v[160:161]
	v_pk_fma_f32 v[160:161], v[66:67], v[186:187], v[162:163]
	v_pk_fma_f32 v[162:163], v[52:53], v[186:187], v[164:165]
	v_pk_fma_f32 v[164:165], v[50:51], v[186:187], v[166:167]
	v_pk_fma_f32 v[166:167], v[48:49], v[186:187], v[168:169]
	v_pk_fma_f32 v[168:169], v[64:65], v[186:187], v[170:171]
	v_pk_fma_f32 v[170:171], v[46:47], v[186:187], v[172:173]
	v_pk_fma_f32 v[172:173], v[44:45], v[186:187], v[174:175]
	v_pk_fma_f32 v[174:175], v[42:43], v[186:187], v[176:177]
	v_pk_fma_f32 v[176:177], v[38:39], v[186:187], v[178:179]
	v_pk_fma_f32 v[178:179], v[40:41], v[186:187], v[180:181]
	v_pk_fma_f32 v[180:181], v[30:31], v[186:187], v[182:183]
	v_pk_fma_f32 v[182:183], v[28:29], v[186:187], v[184:185]
	s_waitcnt vmcnt(17)
	v_lshlrev_b32_e32 v184, 16, v151
	v_and_b32_e32 v185, 0xffff0000, v151
	v_pk_fma_f32 v[152:153], v[60:61], v[184:185], v[152:153]
	v_pk_fma_f32 v[154:155], v[68:69], v[184:185], v[154:155]
	v_pk_fma_f32 v[156:157], v[58:59], v[184:185], v[156:157]
	v_pk_fma_f32 v[158:159], v[56:57], v[184:185], v[158:159]
	v_pk_fma_f32 v[160:161], v[54:55], v[184:185], v[160:161]
	v_pk_fma_f32 v[162:163], v[66:67], v[184:185], v[162:163]
	v_pk_fma_f32 v[164:165], v[52:53], v[184:185], v[164:165]
	v_pk_fma_f32 v[166:167], v[50:51], v[184:185], v[166:167]
	v_pk_fma_f32 v[168:169], v[48:49], v[184:185], v[168:169]
	v_pk_fma_f32 v[170:171], v[64:65], v[184:185], v[170:171]
	v_pk_fma_f32 v[172:173], v[46:47], v[184:185], v[172:173]
	v_pk_fma_f32 v[174:175], v[44:45], v[184:185], v[174:175]
	v_pk_fma_f32 v[176:177], v[42:43], v[184:185], v[176:177]
	v_pk_fma_f32 v[178:179], v[38:39], v[184:185], v[178:179]
	v_pk_fma_f32 v[180:181], v[40:41], v[184:185], v[180:181]
	v_pk_fma_f32 v[182:183], v[30:31], v[184:185], v[182:183]
	s_waitcnt vmcnt(16)
	v_lshlrev_b32_e32 v184, 16, v150
	v_and_b32_e32 v185, 0xffff0000, v150
	v_pk_fma_f32 v[150:151], v[62:63], v[184:185], v[152:153]
	v_pk_fma_f32 v[152:153], v[60:61], v[184:185], v[154:155]
	v_pk_fma_f32 v[154:155], v[68:69], v[184:185], v[156:157]
	v_pk_fma_f32 v[156:157], v[58:59], v[184:185], v[158:159]
	v_pk_fma_f32 v[158:159], v[56:57], v[184:185], v[160:161]
	v_pk_fma_f32 v[160:161], v[54:55], v[184:185], v[162:163]
	v_pk_fma_f32 v[162:163], v[66:67], v[184:185], v[164:165]
	v_pk_fma_f32 v[164:165], v[52:53], v[184:185], v[166:167]
	v_pk_fma_f32 v[166:167], v[50:51], v[184:185], v[168:169]
	v_pk_fma_f32 v[168:169], v[48:49], v[184:185], v[170:171]
	v_pk_fma_f32 v[170:171], v[64:65], v[184:185], v[172:173]
	v_pk_fma_f32 v[172:173], v[46:47], v[184:185], v[174:175]
	v_pk_fma_f32 v[174:175], v[44:45], v[184:185], v[176:177]
	v_pk_fma_f32 v[176:177], v[42:43], v[184:185], v[178:179]
	v_pk_fma_f32 v[178:179], v[38:39], v[184:185], v[180:181]
	v_pk_fma_f32 v[180:181], v[40:41], v[184:185], v[182:183]
	s_waitcnt vmcnt(15)
	v_lshlrev_b32_e32 v182, 16, v149
	v_and_b32_e32 v183, 0xffff0000, v149
	v_pk_fma_f32 v[150:151], v[70:71], v[182:183], v[150:151]
	v_pk_fma_f32 v[152:153], v[62:63], v[182:183], v[152:153]
	v_pk_fma_f32 v[154:155], v[60:61], v[182:183], v[154:155]
	v_pk_fma_f32 v[156:157], v[68:69], v[182:183], v[156:157]
	v_pk_fma_f32 v[158:159], v[58:59], v[182:183], v[158:159]
	v_pk_fma_f32 v[160:161], v[56:57], v[182:183], v[160:161]
	v_pk_fma_f32 v[162:163], v[54:55], v[182:183], v[162:163]
	v_pk_fma_f32 v[164:165], v[66:67], v[182:183], v[164:165]
	v_pk_fma_f32 v[166:167], v[52:53], v[182:183], v[166:167]
	v_pk_fma_f32 v[168:169], v[50:51], v[182:183], v[168:169]
	v_pk_fma_f32 v[170:171], v[48:49], v[182:183], v[170:171]
	v_pk_fma_f32 v[172:173], v[64:65], v[182:183], v[172:173]
	v_pk_fma_f32 v[174:175], v[46:47], v[182:183], v[174:175]
	v_pk_fma_f32 v[176:177], v[44:45], v[182:183], v[176:177]
	v_pk_fma_f32 v[178:179], v[42:43], v[182:183], v[178:179]
	v_pk_fma_f32 v[180:181], v[38:39], v[182:183], v[180:181]
	s_waitcnt vmcnt(14)
	v_lshlrev_b32_e32 v182, 16, v148
	v_and_b32_e32 v183, 0xffff0000, v148
	v_pk_fma_f32 v[148:149], v[70:71], v[182:183], v[152:153]
	v_pk_fma_f32 v[152:153], v[62:63], v[182:183], v[154:155]
	v_pk_fma_f32 v[154:155], v[60:61], v[182:183], v[156:157]
	v_pk_fma_f32 v[156:157], v[68:69], v[182:183], v[158:159]
	v_pk_fma_f32 v[158:159], v[58:59], v[182:183], v[160:161]
	v_pk_fma_f32 v[160:161], v[56:57], v[182:183], v[162:163]
	v_pk_fma_f32 v[162:163], v[54:55], v[182:183], v[164:165]
	v_pk_fma_f32 v[164:165], v[66:67], v[182:183], v[166:167]
	v_pk_fma_f32 v[166:167], v[52:53], v[182:183], v[168:169]
	v_pk_fma_f32 v[168:169], v[50:51], v[182:183], v[170:171]
	v_pk_fma_f32 v[170:171], v[48:49], v[182:183], v[172:173]
	v_pk_fma_f32 v[172:173], v[64:65], v[182:183], v[174:175]
	v_pk_fma_f32 v[174:175], v[46:47], v[182:183], v[176:177]
	v_pk_fma_f32 v[176:177], v[44:45], v[182:183], v[178:179]
	v_pk_fma_f32 v[178:179], v[42:43], v[182:183], v[180:181]
	s_waitcnt vmcnt(13)
	v_lshlrev_b32_e32 v180, 16, v147
	v_and_b32_e32 v181, 0xffff0000, v147
	v_pk_fma_f32 v[152:153], v[70:71], v[180:181], v[152:153]
	v_pk_fma_f32 v[154:155], v[62:63], v[180:181], v[154:155]
	v_pk_fma_f32 v[156:157], v[60:61], v[180:181], v[156:157]
	v_pk_fma_f32 v[158:159], v[68:69], v[180:181], v[158:159]
	v_pk_fma_f32 v[160:161], v[58:59], v[180:181], v[160:161]
	v_pk_fma_f32 v[162:163], v[56:57], v[180:181], v[162:163]
	v_pk_fma_f32 v[164:165], v[54:55], v[180:181], v[164:165]
	v_pk_fma_f32 v[166:167], v[66:67], v[180:181], v[166:167]
	v_pk_fma_f32 v[168:169], v[52:53], v[180:181], v[168:169]
	v_pk_fma_f32 v[170:171], v[50:51], v[180:181], v[170:171]
	v_pk_fma_f32 v[172:173], v[48:49], v[180:181], v[172:173]
	v_pk_fma_f32 v[174:175], v[64:65], v[180:181], v[174:175]
	v_pk_fma_f32 v[176:177], v[46:47], v[180:181], v[176:177]
	v_pk_fma_f32 v[178:179], v[44:45], v[180:181], v[178:179]
	s_waitcnt vmcnt(12)
	v_lshlrev_b32_e32 v180, 16, v146
	v_and_b32_e32 v181, 0xffff0000, v146
	v_pk_fma_f32 v[146:147], v[70:71], v[180:181], v[154:155]
	v_pk_fma_f32 v[154:155], v[62:63], v[180:181], v[156:157]
	v_pk_fma_f32 v[156:157], v[60:61], v[180:181], v[158:159]
	v_pk_fma_f32 v[158:159], v[68:69], v[180:181], v[160:161]
	v_pk_fma_f32 v[160:161], v[58:59], v[180:181], v[162:163]
	v_pk_fma_f32 v[162:163], v[56:57], v[180:181], v[164:165]
	v_pk_fma_f32 v[164:165], v[54:55], v[180:181], v[166:167]
	v_pk_fma_f32 v[166:167], v[66:67], v[180:181], v[168:169]
	v_pk_fma_f32 v[168:169], v[52:53], v[180:181], v[170:171]
	v_pk_fma_f32 v[170:171], v[50:51], v[180:181], v[172:173]
	v_pk_fma_f32 v[172:173], v[48:49], v[180:181], v[174:175]
	v_pk_fma_f32 v[174:175], v[64:65], v[180:181], v[176:177]
	v_pk_fma_f32 v[176:177], v[46:47], v[180:181], v[178:179]
	s_waitcnt vmcnt(11)
	v_lshlrev_b32_e32 v178, 16, v145
	v_and_b32_e32 v179, 0xffff0000, v145
	v_pk_fma_f32 v[154:155], v[70:71], v[178:179], v[154:155]
	v_pk_fma_f32 v[156:157], v[62:63], v[178:179], v[156:157]
	v_pk_fma_f32 v[158:159], v[60:61], v[178:179], v[158:159]
	v_pk_fma_f32 v[160:161], v[68:69], v[178:179], v[160:161]
	v_pk_fma_f32 v[162:163], v[58:59], v[178:179], v[162:163]
	v_pk_fma_f32 v[164:165], v[56:57], v[178:179], v[164:165]
	v_pk_fma_f32 v[166:167], v[54:55], v[178:179], v[166:167]
	v_pk_fma_f32 v[168:169], v[66:67], v[178:179], v[168:169]
	v_pk_fma_f32 v[170:171], v[52:53], v[178:179], v[170:171]
	v_pk_fma_f32 v[172:173], v[50:51], v[178:179], v[172:173]
	v_pk_fma_f32 v[174:175], v[48:49], v[178:179], v[174:175]
	v_pk_fma_f32 v[176:177], v[64:65], v[178:179], v[176:177]
	s_waitcnt vmcnt(10)
	v_lshlrev_b32_e32 v178, 16, v144
	v_and_b32_e32 v179, 0xffff0000, v144
	v_pk_fma_f32 v[144:145], v[70:71], v[178:179], v[156:157]
	v_pk_fma_f32 v[156:157], v[62:63], v[178:179], v[158:159]
	v_pk_fma_f32 v[158:159], v[60:61], v[178:179], v[160:161]
	v_pk_fma_f32 v[160:161], v[68:69], v[178:179], v[162:163]
	v_pk_fma_f32 v[162:163], v[58:59], v[178:179], v[164:165]
	v_pk_fma_f32 v[164:165], v[56:57], v[178:179], v[166:167]
	v_pk_fma_f32 v[166:167], v[54:55], v[178:179], v[168:169]
	v_pk_fma_f32 v[168:169], v[66:67], v[178:179], v[170:171]
	v_pk_fma_f32 v[170:171], v[52:53], v[178:179], v[172:173]
	v_pk_fma_f32 v[172:173], v[50:51], v[178:179], v[174:175]
	v_pk_fma_f32 v[174:175], v[48:49], v[178:179], v[176:177]
	s_waitcnt vmcnt(9)
	v_lshlrev_b32_e32 v176, 16, v143
	v_and_b32_e32 v177, 0xffff0000, v143
	v_pk_fma_f32 v[156:157], v[70:71], v[176:177], v[156:157]
	v_pk_fma_f32 v[158:159], v[62:63], v[176:177], v[158:159]
	v_pk_fma_f32 v[160:161], v[60:61], v[176:177], v[160:161]
	v_pk_fma_f32 v[162:163], v[68:69], v[176:177], v[162:163]
	v_pk_fma_f32 v[164:165], v[58:59], v[176:177], v[164:165]
	v_pk_fma_f32 v[166:167], v[56:57], v[176:177], v[166:167]
	v_pk_fma_f32 v[168:169], v[54:55], v[176:177], v[168:169]
	v_pk_fma_f32 v[170:171], v[66:67], v[176:177], v[170:171]
	v_pk_fma_f32 v[172:173], v[52:53], v[176:177], v[172:173]
	v_pk_fma_f32 v[174:175], v[50:51], v[176:177], v[174:175]
	s_waitcnt vmcnt(8)
	v_lshlrev_b32_e32 v176, 16, v142
	v_and_b32_e32 v177, 0xffff0000, v142
	v_pk_fma_f32 v[142:143], v[70:71], v[176:177], v[158:159]
	v_pk_fma_f32 v[158:159], v[62:63], v[176:177], v[160:161]
	v_pk_fma_f32 v[160:161], v[60:61], v[176:177], v[162:163]
	v_pk_fma_f32 v[162:163], v[68:69], v[176:177], v[164:165]
	v_pk_fma_f32 v[164:165], v[58:59], v[176:177], v[166:167]
	v_pk_fma_f32 v[166:167], v[56:57], v[176:177], v[168:169]
	v_pk_fma_f32 v[168:169], v[54:55], v[176:177], v[170:171]
	v_pk_fma_f32 v[170:171], v[66:67], v[176:177], v[172:173]
	v_pk_fma_f32 v[172:173], v[52:53], v[176:177], v[174:175]
	s_waitcnt vmcnt(7)
	v_lshlrev_b32_e32 v174, 16, v141
	v_and_b32_e32 v175, 0xffff0000, v141
	v_pk_fma_f32 v[158:159], v[70:71], v[174:175], v[158:159]
	v_pk_fma_f32 v[160:161], v[62:63], v[174:175], v[160:161]
	v_pk_fma_f32 v[162:163], v[60:61], v[174:175], v[162:163]
	v_pk_fma_f32 v[164:165], v[68:69], v[174:175], v[164:165]
	v_pk_fma_f32 v[166:167], v[58:59], v[174:175], v[166:167]
	v_pk_fma_f32 v[168:169], v[56:57], v[174:175], v[168:169]
	v_pk_fma_f32 v[170:171], v[54:55], v[174:175], v[170:171]
	v_pk_fma_f32 v[172:173], v[66:67], v[174:175], v[172:173]
	s_waitcnt vmcnt(6)
	v_lshlrev_b32_e32 v174, 16, v139
	v_and_b32_e32 v175, 0xffff0000, v139
	v_pk_fma_f32 v[160:161], v[70:71], v[174:175], v[160:161]
	v_pk_fma_f32 v[162:163], v[62:63], v[174:175], v[162:163]
	v_pk_fma_f32 v[164:165], v[60:61], v[174:175], v[164:165]
	v_pk_fma_f32 v[166:167], v[68:69], v[174:175], v[166:167]
	v_pk_fma_f32 v[168:169], v[58:59], v[174:175], v[168:169]
	v_pk_fma_f32 v[170:171], v[56:57], v[174:175], v[170:171]
	v_pk_fma_f32 v[172:173], v[54:55], v[174:175], v[172:173]
	s_waitcnt vmcnt(5)
	v_lshlrev_b32_e32 v174, 16, v140
	v_and_b32_e32 v175, 0xffff0000, v140
	v_pk_fma_f32 v[140:141], v[70:71], v[174:175], v[162:163]
	v_pk_fma_f32 v[162:163], v[62:63], v[174:175], v[164:165]
	v_pk_fma_f32 v[164:165], v[60:61], v[174:175], v[166:167]
	v_pk_fma_f32 v[166:167], v[68:69], v[174:175], v[168:169]
	v_pk_fma_f32 v[168:169], v[58:59], v[174:175], v[170:171]
	v_pk_fma_f32 v[170:171], v[56:57], v[174:175], v[172:173]
	s_waitcnt vmcnt(4)
	v_lshlrev_b32_e32 v172, 16, v138
	v_and_b32_e32 v173, 0xffff0000, v138
	v_pk_fma_f32 v[138:139], v[70:71], v[172:173], v[162:163]
	v_pk_fma_f32 v[162:163], v[62:63], v[172:173], v[164:165]
	v_pk_fma_f32 v[164:165], v[60:61], v[172:173], v[166:167]
	v_pk_fma_f32 v[166:167], v[68:69], v[172:173], v[168:169]
	v_pk_fma_f32 v[168:169], v[58:59], v[172:173], v[170:171]
	s_waitcnt vmcnt(3)
	v_lshlrev_b32_e32 v170, 16, v137
	v_and_b32_e32 v171, 0xffff0000, v137
	v_pk_fma_f32 v[162:163], v[70:71], v[170:171], v[162:163]
	v_pk_fma_f32 v[164:165], v[62:63], v[170:171], v[164:165]
	v_pk_fma_f32 v[166:167], v[60:61], v[170:171], v[166:167]
	v_pk_fma_f32 v[168:169], v[68:69], v[170:171], v[168:169]
	s_waitcnt vmcnt(2)
	v_lshlrev_b32_e32 v170, 16, v136
	v_and_b32_e32 v171, 0xffff0000, v136
	v_pk_fma_f32 v[136:137], v[70:71], v[170:171], v[164:165]
	v_pk_fma_f32 v[164:165], v[62:63], v[170:171], v[166:167]
	v_pk_fma_f32 v[166:167], v[60:61], v[170:171], v[168:169]
	s_waitcnt vmcnt(1)
	v_lshlrev_b32_e32 v168, 16, v135
	v_and_b32_e32 v169, 0xffff0000, v135
	v_pk_fma_f32 v[164:165], v[70:71], v[168:169], v[164:165]
	v_pk_fma_f32 v[166:167], v[62:63], v[168:169], v[166:167]
	s_waitcnt vmcnt(0)
	v_lshlrev_b32_e32 v168, 16, v80
	v_and_b32_e32 v169, 0xffff0000, v80
	v_mov_b32_e32 v80, s20
	v_pk_fma_f32 v[166:167], v[70:71], v[168:169], v[166:167]
	ds_write2st64_b64 v102, v[150:151], v[148:149] offset0:64 offset1:68
	ds_write2st64_b64 v102, v[152:153], v[146:147] offset0:72 offset1:76
	ds_write2st64_b64 v102, v[154:155], v[144:145] offset0:80 offset1:84
	ds_write2st64_b64 v102, v[156:157], v[142:143] offset0:88 offset1:92
	ds_write2st64_b64 v102, v[158:159], v[160:161] offset0:96 offset1:100
	ds_write2st64_b64 v102, v[140:141], v[138:139] offset0:104 offset1:108
	ds_write2st64_b64 v102, v[162:163], v[136:137] offset0:112 offset1:116
	ds_write2st64_b64 v102, v[164:165], v[166:167] offset0:120 offset1:124
	s_and_saveexec_b64 s[98:99], s[4:5]
	s_cbranch_execz .Lconv_tk
	s_waitcnt vmcnt(0)
	v_mov_b32_e32 v231, s20
	s_nop 0
	ds_write_b32 v231, v230
.Lconv_tk:
	s_or_b64 exec, exec, s[98:99]
	s_waitcnt lgkmcnt(0)
	s_barrier
	ds_read_b32 v135, v80
	v_add_u32_e32 v80, s12, v101
	ds_read_b128 v[136:139], v80
	ds_read_b128 v[140:143], v80 offset:16
	s_add_i32 s10, s8, s6
	s_ashr_i32 s11, s10, 31
	s_waitcnt lgkmcnt(2)
	v_readfirstlane_b32 s9, v135
	s_waitcnt lgkmcnt(1)
	v_add_f32_e32 v80, v136, v137
	v_add_f32_e32 v144, v138, v139
	v_add_f32_e32 v80, v80, v144
	s_waitcnt lgkmcnt(0)
	v_add_f32_e32 v144, v140, v141
	v_add_f32_e32 v80, v80, v144
	v_add_f32_e32 v144, v142, v143
	v_add_f32_e32 v80, v144, v80
	s_lshl_b64 s[10:11], s[10:11], 11
	s_add_u32 s10, s62, s10
	v_add_f32_dpp v80, v80, v80 quad_perm:[1,0,3,2] row_mask:0xf bank_mask:0xf bound_ctrl:1
	s_addc_u32 s11, s63, s11
	s_mov_b32 s29, s2
	v_add_f32_dpp v80, v80, v80 quad_perm:[2,3,0,1] row_mask:0xf bank_mask:0xf bound_ctrl:1
	s_mov_b32 s2, s9
	s_nop 0
	v_add_f32_dpp v80, v80, v80 row_half_mirror row_mask:0xf bank_mask:0xf bound_ctrl:1
	s_nop 1
	v_add_f32_dpp v80, v80, v80 row_mirror row_mask:0xf bank_mask:0xf bound_ctrl:1
	v_mov_b32_e32 v144, v80
	s_nop 1
	v_permlane16_swap_b32_e32 v80, v144
	v_add_f32_e32 v80, v80, v144
	v_mov_b32_e32 v144, v80
	s_nop 1
	v_permlane32_swap_b32_e32 v80, v144
	v_add_f32_e32 v80, v80, v144
	v_fmamk_f32 v139, v80, 0xbb000000, v139
	v_fmac_f32_e32 v137, 0xbb000000, v80
	v_fmamk_f32 v138, v80, 0xbb000000, v138
	v_fmamk_f32 v136, v80, 0xbb000000, v136
	v_fmamk_f32 v142, v80, 0xbb000000, v142
	v_fmamk_f32 v143, v80, 0xbb000000, v143
	v_fmamk_f32 v140, v80, 0xbb000000, v140
	v_fmac_f32_e32 v141, 0xbb000000, v80
	v_mul_f32_e32 v80, v137, v137
	v_mul_f32_e32 v144, v139, v139
	v_fmac_f32_e32 v80, v136, v136
	v_fmac_f32_e32 v144, v138, v138
	v_add_f32_e32 v80, v80, v144
	v_mul_f32_e32 v144, v141, v141
	v_fmac_f32_e32 v144, v140, v140
	v_add_f32_e32 v80, v144, v80
	v_mul_f32_e32 v144, v143, v143
	v_fmac_f32_e32 v144, v142, v142
	v_add_f32_e32 v80, v144, v80
	s_nop 1
	v_add_f32_dpp v80, v80, v80 quad_perm:[1,0,3,2] row_mask:0xf bank_mask:0xf bound_ctrl:1
	s_nop 1
	v_add_f32_dpp v80, v80, v80 quad_perm:[2,3,0,1] row_mask:0xf bank_mask:0xf bound_ctrl:1
	s_nop 1
	v_add_f32_dpp v80, v80, v80 row_half_mirror row_mask:0xf bank_mask:0xf bound_ctrl:1
	s_nop 1
	v_add_f32_dpp v80, v80, v80 row_mirror row_mask:0xf bank_mask:0xf bound_ctrl:1
	v_mov_b32_e32 v144, v80
	s_nop 1
	v_permlane16_swap_b32_e32 v80, v144
	v_add_f32_e32 v80, v80, v144
	v_mov_b32_e32 v144, v80
	s_nop 1
	v_permlane32_swap_b32_e32 v80, v144
	v_add_f32_e32 v80, v80, v144
	v_fmamk_f32 v80, v80, 0x3b000000, v109
	v_rsq_f32_e32 v80, v80
	s_nop 0
	v_pk_mul_f32 v[136:137], v[136:137], v[80:81] op_sel_hi:[1,0]
	s_nop 0
	v_pk_fma_f32 v[136:137], v[8:9], v[136:137], v[12:13]
	v_pk_mul_f32 v[140:141], v[140:141], v[80:81] op_sel_hi:[1,0]
	v_mul_f32_e32 v135, 0xbfb8aa3b, v136
	v_exp_f32_e32 v135, v135
	v_pk_fma_f32 v[140:141], v[0:1], v[140:141], v[4:5]
	v_pk_mul_f32 v[138:139], v[138:139], v[80:81] op_sel_hi:[1,0]
	v_pk_mul_f32 v[142:143], v[142:143], v[80:81] op_sel_hi:[1,0]
	v_add_f32_e32 v80, 1.0, v135
	v_mul_f32_e32 v135, 0xbfb8aa3b, v140
	v_mul_f32_e32 v144, 0xbfb8aa3b, v137
	v_exp_f32_e32 v135, v135
	v_exp_f32_e32 v144, v144
	v_mul_f32_e32 v145, 0xbfb8aa3b, v141
	v_rcp_f32_e32 v80, v80
	v_add_f32_e32 v135, 1.0, v135
	v_add_f32_e32 v144, 1.0, v144
	v_rcp_f32_e32 v135, v135
	v_rcp_f32_e32 v144, v144
	v_exp_f32_e32 v145, v145
	v_pk_fma_f32 v[138:139], v[10:11], v[138:139], v[14:15]
	v_pk_fma_f32 v[142:143], v[2:3], v[142:143], v[6:7]
	v_mul_f32_e32 v80, v136, v80
	v_mul_f32_e32 v135, v140, v135
	v_mul_f32_e32 v136, v137, v144
	v_add_f32_e32 v137, 1.0, v145
	v_mul_f32_e32 v140, 0xbfb8aa3b, v138
	v_mul_f32_e32 v144, 0xbfb8aa3b, v142
	v_rcp_f32_e32 v137, v137
	v_exp_f32_e32 v140, v140
	v_exp_f32_e32 v144, v144
	v_mul_f32_e32 v145, 0xbfb8aa3b, v143
	v_mul_f32_e32 v141, v141, v137
	v_add_f32_e32 v137, 1.0, v140
	v_add_f32_e32 v140, 1.0, v144
	v_mul_f32_e32 v144, 0xbfb8aa3b, v139
	v_exp_f32_e32 v144, v144
	v_exp_f32_e32 v145, v145
	v_rcp_f32_e32 v137, v137
	v_rcp_f32_e32 v140, v140
	v_add_f32_e32 v144, 1.0, v144
	v_rcp_f32_e32 v144, v144
	v_add_f32_e32 v145, 1.0, v145
	v_rcp_f32_e32 v145, v145
	v_mul_f32_e32 v137, v138, v137
	v_mul_f32_e32 v138, v139, v144
	v_mul_f32_e32 v140, v142, v140
	v_mul_f32_e32 v139, v143, v145
	v_cvt_pk_bf16_f32 v136, v80, v136
	v_cvt_pk_bf16_f32 v137, v137, v138
	v_cvt_pk_bf16_f32 v138, v135, v141
	v_add_u32_e32 v135, s14, v101
	v_cvt_pk_bf16_f32 v139, v140, v139
	ds_read_b128 v[140:143], v135
	ds_read_b128 v[144:147], v135 offset:16
	v_lshlrev_b32_e32 v80, 1, v84
	v_lshl_add_u64 v[148:149], s[10:11], 0, v[80:81]
	v_add_co_u32_e32 v148, vcc, s28, v148
	s_waitcnt lgkmcnt(1)
	v_add_f32_e32 v135, v140, v141
	v_add_f32_e32 v150, v142, v143
	v_add_f32_e32 v135, v135, v150
	s_waitcnt lgkmcnt(0)
	v_add_f32_e32 v150, v144, v145
	v_add_f32_e32 v135, v135, v150
	v_add_f32_e32 v150, v146, v147
	v_add_f32_e32 v135, v150, v135
	v_addc_co_u32_e32 v149, vcc, 0, v149, vcc
	s_nop 0
	v_add_f32_dpp v135, v135, v135 quad_perm:[1,0,3,2] row_mask:0xf bank_mask:0xf bound_ctrl:1
	global_store_dwordx4 v[148:149], v[136:139], off offset:1024
	s_add_i32 s10, s8, s13
	v_add_f32_dpp v135, v135, v135 quad_perm:[2,3,0,1] row_mask:0xf bank_mask:0xf bound_ctrl:1
	s_ashr_i32 s11, s10, 31
	s_lshl_b64 s[10:11], s[10:11], 11
	v_add_f32_dpp v135, v135, v135 row_half_mirror row_mask:0xf bank_mask:0xf bound_ctrl:1
	s_add_u32 s10, s62, s10
	s_addc_u32 s11, s63, s11
	v_add_f32_dpp v135, v135, v135 row_mirror row_mask:0xf bank_mask:0xf bound_ctrl:1
	v_mov_b32_e32 v150, v135
	s_nop 1
	v_permlane16_swap_b32_e32 v135, v150
	v_add_f32_e32 v135, v135, v150
	v_mov_b32_e32 v150, v135
	s_nop 1
	v_permlane32_swap_b32_e32 v135, v150
	v_add_f32_e32 v135, v135, v150
	v_fmamk_f32 v143, v135, 0xbb000000, v143
	v_fmac_f32_e32 v141, 0xbb000000, v135
	v_fmamk_f32 v142, v135, 0xbb000000, v142
	v_fmamk_f32 v140, v135, 0xbb000000, v140
	v_fmamk_f32 v146, v135, 0xbb000000, v146
	v_fmamk_f32 v147, v135, 0xbb000000, v147
	v_fmamk_f32 v144, v135, 0xbb000000, v144
	v_fmac_f32_e32 v145, 0xbb000000, v135
	v_mul_f32_e32 v135, v141, v141
	v_mul_f32_e32 v150, v143, v143
	v_fmac_f32_e32 v135, v140, v140
	v_fmac_f32_e32 v150, v142, v142
	v_add_f32_e32 v135, v135, v150
	v_mul_f32_e32 v150, v145, v145
	v_fmac_f32_e32 v150, v144, v144
	v_add_f32_e32 v135, v150, v135
	v_mul_f32_e32 v150, v147, v147
	v_fmac_f32_e32 v150, v146, v146
	v_add_f32_e32 v135, v150, v135
	v_lshl_add_u64 v[148:149], s[10:11], 0, v[80:81]
	v_add_co_u32_e32 v148, vcc, s28, v148
	v_add_f32_dpp v135, v135, v135 quad_perm:[1,0,3,2] row_mask:0xf bank_mask:0xf bound_ctrl:1
	s_nop 0
	v_addc_co_u32_e32 v149, vcc, 0, v149, vcc
	v_add_f32_dpp v135, v135, v135 quad_perm:[2,3,0,1] row_mask:0xf bank_mask:0xf bound_ctrl:1
	s_add_i32 s10, s8, s15
	s_ashr_i32 s11, s10, 31
	v_add_f32_dpp v135, v135, v135 row_half_mirror row_mask:0xf bank_mask:0xf bound_ctrl:1
	s_lshl_b64 s[10:11], s[10:11], 11
	s_add_u32 s10, s62, s10
	v_add_f32_dpp v135, v135, v135 row_mirror row_mask:0xf bank_mask:0xf bound_ctrl:1
	v_mov_b32_e32 v150, v135
	s_nop 1
	v_permlane16_swap_b32_e32 v135, v150
	v_add_f32_e32 v135, v135, v150
	v_mov_b32_e32 v150, v135
	s_nop 1
	v_permlane32_swap_b32_e32 v135, v150
	v_add_f32_e32 v135, v135, v150
	v_fmamk_f32 v135, v135, 0x3b000000, v109
	v_rsq_f32_e32 v150, v135
	s_addc_u32 s11, s63, s11
	v_pk_mul_f32 v[136:137], v[140:141], v[150:151] op_sel_hi:[1,0]
	v_pk_mul_f32 v[140:141], v[144:145], v[150:151] op_sel_hi:[1,0]
	v_pk_fma_f32 v[136:137], v[8:9], v[136:137], v[12:13]
	v_pk_fma_f32 v[140:141], v[0:1], v[140:141], v[4:5]
	v_mul_f32_e32 v135, 0xbfb8aa3b, v136
	v_mul_f32_e32 v144, 0xbfb8aa3b, v140
	v_mul_f32_e32 v145, 0xbfb8aa3b, v137
	v_exp_f32_e32 v135, v135
	v_exp_f32_e32 v144, v144
	v_exp_f32_e32 v145, v145
	v_pk_mul_f32 v[138:139], v[142:143], v[150:151] op_sel_hi:[1,0]
	v_pk_mul_f32 v[142:143], v[146:147], v[150:151] op_sel_hi:[1,0]
	v_add_f32_e32 v135, 1.0, v135
	v_add_f32_e32 v144, 1.0, v144
	v_add_f32_e32 v145, 1.0, v145
	v_mul_f32_e32 v146, 0xbfb8aa3b, v141
	v_rcp_f32_e32 v135, v135
	v_rcp_f32_e32 v144, v144
	v_rcp_f32_e32 v145, v145
	v_exp_f32_e32 v146, v146
	v_pk_fma_f32 v[138:139], v[10:11], v[138:139], v[14:15]
	v_pk_fma_f32 v[142:143], v[2:3], v[142:143], v[6:7]
	v_mul_f32_e32 v135, v136, v135
	v_mul_f32_e32 v140, v140, v144
	v_mul_f32_e32 v136, v137, v145
	v_add_f32_e32 v137, 1.0, v146
	v_mul_f32_e32 v144, 0xbfb8aa3b, v138
	v_mul_f32_e32 v145, 0xbfb8aa3b, v142
	v_rcp_f32_e32 v137, v137
	v_exp_f32_e32 v144, v144
	v_exp_f32_e32 v145, v145
	v_mul_f32_e32 v146, 0xbfb8aa3b, v143
	v_mul_f32_e32 v141, v141, v137
	v_add_f32_e32 v137, 1.0, v144
	v_add_f32_e32 v144, 1.0, v145
	v_mul_f32_e32 v145, 0xbfb8aa3b, v139
	v_exp_f32_e32 v145, v145
	v_exp_f32_e32 v146, v146
	v_rcp_f32_e32 v137, v137
	v_rcp_f32_e32 v144, v144
	v_add_f32_e32 v145, 1.0, v145
	v_add_f32_e32 v146, 1.0, v146
	v_rcp_f32_e32 v145, v145
	v_rcp_f32_e32 v146, v146
	v_mul_f32_e32 v137, v138, v137
	v_mul_f32_e32 v142, v142, v144
	v_mul_f32_e32 v138, v139, v145
	v_mul_f32_e32 v139, v143, v146
	v_cvt_pk_bf16_f32 v136, v135, v136
	v_add_u32_e32 v135, s16, v101
	v_cvt_pk_bf16_f32 v137, v137, v138
	v_cvt_pk_bf16_f32 v138, v140, v141
	v_cvt_pk_bf16_f32 v139, v142, v139
	ds_read_b128 v[140:143], v135
	ds_read_b128 v[144:147], v135 offset:16
	global_store_dwordx4 v[148:149], v[136:139], off offset:1024
	v_lshl_add_u64 v[148:149], s[10:11], 0, v[80:81]
	v_add_co_u32_e32 v148, vcc, s28, v148
	s_waitcnt lgkmcnt(1)
	v_add_f32_e32 v135, v140, v141
	v_add_f32_e32 v150, v142, v143
	v_add_f32_e32 v135, v135, v150
	s_waitcnt lgkmcnt(0)
	v_add_f32_e32 v150, v144, v145
	v_add_f32_e32 v135, v135, v150
	v_add_f32_e32 v150, v146, v147
	v_add_f32_e32 v135, v150, v135
	v_addc_co_u32_e32 v149, vcc, 0, v149, vcc
	s_nop 0
	v_add_f32_dpp v135, v135, v135 quad_perm:[1,0,3,2] row_mask:0xf bank_mask:0xf bound_ctrl:1
	s_add_i32 s10, s8, s17
	s_ashr_i32 s11, s10, 31
	v_add_f32_dpp v135, v135, v135 quad_perm:[2,3,0,1] row_mask:0xf bank_mask:0xf bound_ctrl:1
	s_lshl_b64 s[10:11], s[10:11], 11
	s_add_u32 s10, s62, s10
	v_add_f32_dpp v135, v135, v135 row_half_mirror row_mask:0xf bank_mask:0xf bound_ctrl:1
	s_addc_u32 s11, s63, s11
	s_nop 0
	v_add_f32_dpp v135, v135, v135 row_mirror row_mask:0xf bank_mask:0xf bound_ctrl:1
	v_mov_b32_e32 v150, v135
	s_nop 1
	v_permlane16_swap_b32_e32 v135, v150
	v_add_f32_e32 v135, v135, v150
	v_mov_b32_e32 v150, v135
	s_nop 1
	v_permlane32_swap_b32_e32 v135, v150
	v_add_f32_e32 v135, v135, v150
	v_fmamk_f32 v143, v135, 0xbb000000, v143
	v_fmac_f32_e32 v141, 0xbb000000, v135
	v_fmamk_f32 v142, v135, 0xbb000000, v142
	v_fmamk_f32 v140, v135, 0xbb000000, v140
	v_fmamk_f32 v146, v135, 0xbb000000, v146
	v_fmamk_f32 v147, v135, 0xbb000000, v147
	v_fmamk_f32 v144, v135, 0xbb000000, v144
	v_fmac_f32_e32 v145, 0xbb000000, v135
	v_mul_f32_e32 v135, v141, v141
	v_mul_f32_e32 v150, v143, v143
	v_fmac_f32_e32 v135, v140, v140
	v_fmac_f32_e32 v150, v142, v142
	v_add_f32_e32 v135, v135, v150
	v_mul_f32_e32 v150, v145, v145
	v_fmac_f32_e32 v150, v144, v144
	v_add_f32_e32 v135, v150, v135
	v_mul_f32_e32 v150, v147, v147
	v_fmac_f32_e32 v150, v146, v146
	v_add_f32_e32 v135, v150, v135
	s_nop 1
	v_add_f32_dpp v135, v135, v135 quad_perm:[1,0,3,2] row_mask:0xf bank_mask:0xf bound_ctrl:1
	s_nop 1
	v_add_f32_dpp v135, v135, v135 quad_perm:[2,3,0,1] row_mask:0xf bank_mask:0xf bound_ctrl:1
	s_nop 1
	v_add_f32_dpp v135, v135, v135 row_half_mirror row_mask:0xf bank_mask:0xf bound_ctrl:1
	s_nop 1
	v_add_f32_dpp v135, v135, v135 row_mirror row_mask:0xf bank_mask:0xf bound_ctrl:1
	v_mov_b32_e32 v150, v135
	s_nop 1
	v_permlane16_swap_b32_e32 v135, v150
	v_add_f32_e32 v135, v135, v150
	v_mov_b32_e32 v150, v135
	s_nop 1
	v_permlane32_swap_b32_e32 v135, v150
	v_add_f32_e32 v135, v135, v150
	v_fmamk_f32 v135, v135, 0x3b000000, v109
	v_rsq_f32_e32 v150, v135
	s_nop 0
	v_pk_mul_f32 v[136:137], v[140:141], v[150:151] op_sel_hi:[1,0]
	v_pk_mul_f32 v[140:141], v[144:145], v[150:151] op_sel_hi:[1,0]
	v_pk_fma_f32 v[136:137], v[8:9], v[136:137], v[12:13]
	v_pk_fma_f32 v[140:141], v[0:1], v[140:141], v[4:5]
	v_mul_f32_e32 v135, 0xbfb8aa3b, v136
	v_mul_f32_e32 v144, 0xbfb8aa3b, v140
	v_mul_f32_e32 v145, 0xbfb8aa3b, v137
	v_exp_f32_e32 v135, v135
	v_exp_f32_e32 v144, v144
	v_exp_f32_e32 v145, v145
	v_pk_mul_f32 v[138:139], v[142:143], v[150:151] op_sel_hi:[1,0]
	v_pk_mul_f32 v[142:143], v[146:147], v[150:151] op_sel_hi:[1,0]
	v_add_f32_e32 v135, 1.0, v135
	v_add_f32_e32 v144, 1.0, v144
	v_add_f32_e32 v145, 1.0, v145
	v_mul_f32_e32 v146, 0xbfb8aa3b, v141
	v_rcp_f32_e32 v135, v135
	v_rcp_f32_e32 v144, v144
	v_rcp_f32_e32 v145, v145
	v_exp_f32_e32 v146, v146
	v_pk_fma_f32 v[138:139], v[10:11], v[138:139], v[14:15]
	v_pk_fma_f32 v[142:143], v[2:3], v[142:143], v[6:7]
	v_mul_f32_e32 v135, v136, v135
	v_mul_f32_e32 v140, v140, v144
	v_mul_f32_e32 v136, v137, v145
	v_add_f32_e32 v137, 1.0, v146
	v_mul_f32_e32 v144, 0xbfb8aa3b, v138
	v_mul_f32_e32 v145, 0xbfb8aa3b, v142
	v_rcp_f32_e32 v137, v137
	v_exp_f32_e32 v144, v144
	v_exp_f32_e32 v145, v145
	v_mul_f32_e32 v146, 0xbfb8aa3b, v143
	v_mul_f32_e32 v141, v141, v137
	v_add_f32_e32 v137, 1.0, v144
	v_add_f32_e32 v144, 1.0, v145
	v_mul_f32_e32 v145, 0xbfb8aa3b, v139
	v_exp_f32_e32 v145, v145
	v_exp_f32_e32 v146, v146
	v_rcp_f32_e32 v137, v137
	v_rcp_f32_e32 v144, v144
	v_add_f32_e32 v145, 1.0, v145
	v_add_f32_e32 v146, 1.0, v146
	v_rcp_f32_e32 v145, v145
	v_rcp_f32_e32 v146, v146
	v_mul_f32_e32 v137, v138, v137
	v_mul_f32_e32 v142, v142, v144
	v_mul_f32_e32 v138, v139, v145
	v_mul_f32_e32 v139, v143, v146
	v_cvt_pk_bf16_f32 v136, v135, v136
	v_add_u32_e32 v135, s18, v101
	v_cvt_pk_bf16_f32 v137, v137, v138
	v_cvt_pk_bf16_f32 v138, v140, v141
	v_cvt_pk_bf16_f32 v139, v142, v139
	ds_read_b128 v[140:143], v135
	ds_read_b128 v[144:147], v135 offset:16
	global_store_dwordx4 v[148:149], v[136:139], off offset:1024
	v_lshl_add_u64 v[148:149], s[10:11], 0, v[80:81]
	v_add_co_u32_e32 v148, vcc, s28, v148
	s_waitcnt lgkmcnt(1)
	v_add_f32_e32 v135, v140, v141
	v_add_f32_e32 v150, v142, v143
	v_add_f32_e32 v135, v135, v150
	s_waitcnt lgkmcnt(0)
	v_add_f32_e32 v150, v144, v145
	v_add_f32_e32 v135, v135, v150
	v_add_f32_e32 v150, v146, v147
	v_add_f32_e32 v135, v150, v135
	v_addc_co_u32_e32 v149, vcc, 0, v149, vcc
	s_nop 0
	v_add_f32_dpp v135, v135, v135 quad_perm:[1,0,3,2] row_mask:0xf bank_mask:0xf bound_ctrl:1
	s_add_i32 s10, s8, s19
	s_ashr_i32 s11, s10, 31
	v_add_f32_dpp v135, v135, v135 quad_perm:[2,3,0,1] row_mask:0xf bank_mask:0xf bound_ctrl:1
	s_lshl_b64 s[10:11], s[10:11], 11
	s_add_u32 s10, s62, s10
	v_add_f32_dpp v135, v135, v135 row_half_mirror row_mask:0xf bank_mask:0xf bound_ctrl:1
	s_addc_u32 s11, s63, s11
	s_nop 0
	v_add_f32_dpp v135, v135, v135 row_mirror row_mask:0xf bank_mask:0xf bound_ctrl:1
	v_mov_b32_e32 v150, v135
	s_nop 1
	v_permlane16_swap_b32_e32 v135, v150
	v_add_f32_e32 v135, v135, v150
	v_mov_b32_e32 v150, v135
	s_nop 1
	v_permlane32_swap_b32_e32 v135, v150
	v_add_f32_e32 v135, v135, v150
	v_fmamk_f32 v143, v135, 0xbb000000, v143
	v_fmac_f32_e32 v141, 0xbb000000, v135
	v_fmamk_f32 v142, v135, 0xbb000000, v142
	v_fmamk_f32 v140, v135, 0xbb000000, v140
	v_fmamk_f32 v146, v135, 0xbb000000, v146
	v_fmamk_f32 v147, v135, 0xbb000000, v147
	v_fmamk_f32 v144, v135, 0xbb000000, v144
	v_fmac_f32_e32 v145, 0xbb000000, v135
	v_mul_f32_e32 v135, v141, v141
	v_mul_f32_e32 v150, v143, v143
	v_fmac_f32_e32 v135, v140, v140
	v_fmac_f32_e32 v150, v142, v142
	v_add_f32_e32 v135, v135, v150
	v_mul_f32_e32 v150, v145, v145
	v_fmac_f32_e32 v150, v144, v144
	v_add_f32_e32 v135, v150, v135
	v_mul_f32_e32 v150, v147, v147
	v_fmac_f32_e32 v150, v146, v146
	v_add_f32_e32 v135, v150, v135
	s_nop 1
	v_add_f32_dpp v135, v135, v135 quad_perm:[1,0,3,2] row_mask:0xf bank_mask:0xf bound_ctrl:1
	s_nop 1
	v_add_f32_dpp v135, v135, v135 quad_perm:[2,3,0,1] row_mask:0xf bank_mask:0xf bound_ctrl:1
	s_nop 1
	v_add_f32_dpp v135, v135, v135 row_half_mirror row_mask:0xf bank_mask:0xf bound_ctrl:1
	s_nop 1
	v_add_f32_dpp v135, v135, v135 row_mirror row_mask:0xf bank_mask:0xf bound_ctrl:1
	v_mov_b32_e32 v150, v135
	s_nop 1
	v_permlane16_swap_b32_e32 v135, v150
	v_add_f32_e32 v135, v135, v150
	v_mov_b32_e32 v150, v135
	s_nop 1
	v_permlane32_swap_b32_e32 v135, v150
	v_add_f32_e32 v135, v135, v150
	v_fmamk_f32 v135, v135, 0x3b000000, v109
	v_rsq_f32_e32 v150, v135
	s_nop 0
	v_pk_mul_f32 v[136:137], v[140:141], v[150:151] op_sel_hi:[1,0]
	v_pk_mul_f32 v[140:141], v[144:145], v[150:151] op_sel_hi:[1,0]
	v_pk_fma_f32 v[136:137], v[8:9], v[136:137], v[12:13]
	v_pk_fma_f32 v[140:141], v[0:1], v[140:141], v[4:5]
	v_mul_f32_e32 v135, 0xbfb8aa3b, v136
	v_mul_f32_e32 v144, 0xbfb8aa3b, v140
	v_mul_f32_e32 v145, 0xbfb8aa3b, v137
	v_exp_f32_e32 v135, v135
	v_exp_f32_e32 v144, v144
	v_exp_f32_e32 v145, v145
	v_pk_mul_f32 v[138:139], v[142:143], v[150:151] op_sel_hi:[1,0]
	v_pk_mul_f32 v[142:143], v[146:147], v[150:151] op_sel_hi:[1,0]
	v_add_f32_e32 v135, 1.0, v135
	v_add_f32_e32 v144, 1.0, v144
	v_add_f32_e32 v145, 1.0, v145
	v_mul_f32_e32 v146, 0xbfb8aa3b, v141
	v_rcp_f32_e32 v135, v135
	v_rcp_f32_e32 v144, v144
	v_rcp_f32_e32 v145, v145
	v_exp_f32_e32 v146, v146
	v_pk_fma_f32 v[138:139], v[10:11], v[138:139], v[14:15]
	v_pk_fma_f32 v[142:143], v[2:3], v[142:143], v[6:7]
	v_mul_f32_e32 v135, v136, v135
	v_mul_f32_e32 v140, v140, v144
	v_mul_f32_e32 v136, v137, v145
	v_add_f32_e32 v137, 1.0, v146
	v_mul_f32_e32 v144, 0xbfb8aa3b, v138
	v_mul_f32_e32 v145, 0xbfb8aa3b, v142
	v_rcp_f32_e32 v137, v137
	v_exp_f32_e32 v144, v144
	v_exp_f32_e32 v145, v145
	v_mul_f32_e32 v146, 0xbfb8aa3b, v143
	v_mul_f32_e32 v141, v141, v137
	v_add_f32_e32 v137, 1.0, v144
	v_add_f32_e32 v144, 1.0, v145
	v_mul_f32_e32 v145, 0xbfb8aa3b, v139
	v_exp_f32_e32 v145, v145
	v_exp_f32_e32 v146, v146
	v_rcp_f32_e32 v137, v137
	v_rcp_f32_e32 v144, v144
	v_add_f32_e32 v145, 1.0, v145
	v_add_f32_e32 v146, 1.0, v146
	v_rcp_f32_e32 v145, v145
	v_rcp_f32_e32 v146, v146
	v_mul_f32_e32 v137, v138, v137
	v_mul_f32_e32 v142, v142, v144
	v_mul_f32_e32 v138, v139, v145
	v_mul_f32_e32 v139, v143, v146
	v_cvt_pk_bf16_f32 v136, v135, v136
	v_add_u32_e32 v135, s21, v101
	v_cvt_pk_bf16_f32 v137, v137, v138
	v_cvt_pk_bf16_f32 v138, v140, v141
	v_cvt_pk_bf16_f32 v139, v142, v139
	ds_read_b128 v[140:143], v135
	ds_read_b128 v[144:147], v135 offset:16
	global_store_dwordx4 v[148:149], v[136:139], off offset:1024
	v_lshl_add_u64 v[148:149], s[10:11], 0, v[80:81]
	v_add_co_u32_e32 v148, vcc, s28, v148
	s_waitcnt lgkmcnt(1)
	v_add_f32_e32 v135, v140, v141
	v_add_f32_e32 v150, v142, v143
	v_add_f32_e32 v135, v135, v150
	s_waitcnt lgkmcnt(0)
	v_add_f32_e32 v150, v144, v145
	v_add_f32_e32 v135, v135, v150
	v_add_f32_e32 v150, v146, v147
	v_add_f32_e32 v135, v150, v135
	v_addc_co_u32_e32 v149, vcc, 0, v149, vcc
	s_nop 0
	v_add_f32_dpp v135, v135, v135 quad_perm:[1,0,3,2] row_mask:0xf bank_mask:0xf bound_ctrl:1
	s_add_i32 s10, s8, s22
	s_ashr_i32 s11, s10, 31
	v_add_f32_dpp v135, v135, v135 quad_perm:[2,3,0,1] row_mask:0xf bank_mask:0xf bound_ctrl:1
	s_lshl_b64 s[10:11], s[10:11], 11
	s_add_u32 s10, s62, s10
	v_add_f32_dpp v135, v135, v135 row_half_mirror row_mask:0xf bank_mask:0xf bound_ctrl:1
	s_addc_u32 s11, s63, s11
	s_nop 0
	v_add_f32_dpp v135, v135, v135 row_mirror row_mask:0xf bank_mask:0xf bound_ctrl:1
	v_mov_b32_e32 v150, v135
	s_nop 1
	v_permlane16_swap_b32_e32 v135, v150
	v_add_f32_e32 v135, v135, v150
	v_mov_b32_e32 v150, v135
	s_nop 1
	v_permlane32_swap_b32_e32 v135, v150
	v_add_f32_e32 v135, v135, v150
	v_fmamk_f32 v143, v135, 0xbb000000, v143
	v_fmac_f32_e32 v141, 0xbb000000, v135
	v_fmamk_f32 v142, v135, 0xbb000000, v142
	v_fmamk_f32 v140, v135, 0xbb000000, v140
	v_fmamk_f32 v146, v135, 0xbb000000, v146
	v_fmamk_f32 v147, v135, 0xbb000000, v147
	v_fmamk_f32 v144, v135, 0xbb000000, v144
	v_fmac_f32_e32 v145, 0xbb000000, v135
	v_mul_f32_e32 v135, v141, v141
	v_mul_f32_e32 v150, v143, v143
	v_fmac_f32_e32 v135, v140, v140
	v_fmac_f32_e32 v150, v142, v142
	v_add_f32_e32 v135, v135, v150
	v_mul_f32_e32 v150, v145, v145
	v_fmac_f32_e32 v150, v144, v144
	v_add_f32_e32 v135, v150, v135
	v_mul_f32_e32 v150, v147, v147
	v_fmac_f32_e32 v150, v146, v146
	v_add_f32_e32 v135, v150, v135
	s_nop 1
	v_add_f32_dpp v135, v135, v135 quad_perm:[1,0,3,2] row_mask:0xf bank_mask:0xf bound_ctrl:1
	s_nop 1
	v_add_f32_dpp v135, v135, v135 quad_perm:[2,3,0,1] row_mask:0xf bank_mask:0xf bound_ctrl:1
	s_nop 1
	v_add_f32_dpp v135, v135, v135 row_half_mirror row_mask:0xf bank_mask:0xf bound_ctrl:1
	s_nop 1
	v_add_f32_dpp v135, v135, v135 row_mirror row_mask:0xf bank_mask:0xf bound_ctrl:1
	v_mov_b32_e32 v150, v135
	s_nop 1
	v_permlane16_swap_b32_e32 v135, v150
	v_add_f32_e32 v135, v135, v150
	v_mov_b32_e32 v150, v135
	s_nop 1
	v_permlane32_swap_b32_e32 v135, v150
	v_add_f32_e32 v135, v135, v150
	v_fmamk_f32 v135, v135, 0x3b000000, v109
	v_rsq_f32_e32 v150, v135
	s_nop 0
	v_pk_mul_f32 v[136:137], v[140:141], v[150:151] op_sel_hi:[1,0]
	v_pk_mul_f32 v[140:141], v[144:145], v[150:151] op_sel_hi:[1,0]
	v_pk_fma_f32 v[136:137], v[8:9], v[136:137], v[12:13]
	v_pk_fma_f32 v[140:141], v[0:1], v[140:141], v[4:5]
	v_mul_f32_e32 v135, 0xbfb8aa3b, v136
	v_mul_f32_e32 v144, 0xbfb8aa3b, v140
	v_mul_f32_e32 v145, 0xbfb8aa3b, v137
	v_exp_f32_e32 v135, v135
	v_exp_f32_e32 v144, v144
	v_exp_f32_e32 v145, v145
	v_pk_mul_f32 v[138:139], v[142:143], v[150:151] op_sel_hi:[1,0]
	v_pk_mul_f32 v[142:143], v[146:147], v[150:151] op_sel_hi:[1,0]
	v_add_f32_e32 v135, 1.0, v135
	v_add_f32_e32 v144, 1.0, v144
	v_add_f32_e32 v145, 1.0, v145
	v_mul_f32_e32 v146, 0xbfb8aa3b, v141
	v_rcp_f32_e32 v135, v135
	v_rcp_f32_e32 v144, v144
	v_rcp_f32_e32 v145, v145
	v_exp_f32_e32 v146, v146
	v_pk_fma_f32 v[138:139], v[10:11], v[138:139], v[14:15]
	v_pk_fma_f32 v[142:143], v[2:3], v[142:143], v[6:7]
	v_mul_f32_e32 v135, v136, v135
	v_mul_f32_e32 v140, v140, v144
	v_mul_f32_e32 v136, v137, v145
	v_add_f32_e32 v137, 1.0, v146
	v_mul_f32_e32 v144, 0xbfb8aa3b, v138
	v_mul_f32_e32 v145, 0xbfb8aa3b, v142
	v_rcp_f32_e32 v137, v137
	v_exp_f32_e32 v144, v144
	v_exp_f32_e32 v145, v145
	v_mul_f32_e32 v146, 0xbfb8aa3b, v143
	v_mul_f32_e32 v141, v141, v137
	v_add_f32_e32 v137, 1.0, v144
	v_add_f32_e32 v144, 1.0, v145
	v_mul_f32_e32 v145, 0xbfb8aa3b, v139
	v_exp_f32_e32 v145, v145
	v_exp_f32_e32 v146, v146
	v_rcp_f32_e32 v137, v137
	v_rcp_f32_e32 v144, v144
	v_add_f32_e32 v145, 1.0, v145
	v_add_f32_e32 v146, 1.0, v146
	v_rcp_f32_e32 v145, v145
	v_rcp_f32_e32 v146, v146
	v_mul_f32_e32 v137, v138, v137
	v_mul_f32_e32 v142, v142, v144
	v_mul_f32_e32 v138, v139, v145
	v_mul_f32_e32 v139, v143, v146
	v_cvt_pk_bf16_f32 v136, v135, v136
	v_add_u32_e32 v135, s23, v101
	v_cvt_pk_bf16_f32 v137, v137, v138
	v_cvt_pk_bf16_f32 v138, v140, v141
	v_cvt_pk_bf16_f32 v139, v142, v139
	ds_read_b128 v[140:143], v135
	ds_read_b128 v[144:147], v135 offset:16
	global_store_dwordx4 v[148:149], v[136:139], off offset:1024
	v_lshl_add_u64 v[148:149], s[10:11], 0, v[80:81]
	v_add_co_u32_e32 v148, vcc, s28, v148
	s_waitcnt lgkmcnt(1)
	v_add_f32_e32 v135, v140, v141
	v_add_f32_e32 v150, v142, v143
	v_add_f32_e32 v135, v135, v150
	s_waitcnt lgkmcnt(0)
	v_add_f32_e32 v150, v144, v145
	v_add_f32_e32 v135, v135, v150
	v_add_f32_e32 v150, v146, v147
	v_add_f32_e32 v135, v150, v135
	v_addc_co_u32_e32 v149, vcc, 0, v149, vcc
	s_nop 0
	v_add_f32_dpp v135, v135, v135 quad_perm:[1,0,3,2] row_mask:0xf bank_mask:0xf bound_ctrl:1
	s_add_i32 s10, s8, s24
	s_ashr_i32 s11, s10, 31
	v_add_f32_dpp v135, v135, v135 quad_perm:[2,3,0,1] row_mask:0xf bank_mask:0xf bound_ctrl:1
	s_lshl_b64 s[10:11], s[10:11], 11
	s_add_u32 s10, s62, s10
	v_add_f32_dpp v135, v135, v135 row_half_mirror row_mask:0xf bank_mask:0xf bound_ctrl:1
	s_addc_u32 s11, s63, s11
	s_nop 0
	v_add_f32_dpp v135, v135, v135 row_mirror row_mask:0xf bank_mask:0xf bound_ctrl:1
	v_mov_b32_e32 v150, v135
	s_nop 1
	v_permlane16_swap_b32_e32 v135, v150
	v_add_f32_e32 v135, v135, v150
	v_mov_b32_e32 v150, v135
	s_nop 1
	v_permlane32_swap_b32_e32 v135, v150
	v_add_f32_e32 v135, v135, v150
	v_fmamk_f32 v143, v135, 0xbb000000, v143
	v_fmac_f32_e32 v141, 0xbb000000, v135
	v_fmamk_f32 v142, v135, 0xbb000000, v142
	v_fmamk_f32 v140, v135, 0xbb000000, v140
	v_fmamk_f32 v146, v135, 0xbb000000, v146
	v_fmamk_f32 v147, v135, 0xbb000000, v147
	v_fmamk_f32 v144, v135, 0xbb000000, v144
	v_fmac_f32_e32 v145, 0xbb000000, v135
	v_mul_f32_e32 v135, v141, v141
	v_mul_f32_e32 v150, v143, v143
	v_fmac_f32_e32 v135, v140, v140
	v_fmac_f32_e32 v150, v142, v142
	v_add_f32_e32 v135, v135, v150
	v_mul_f32_e32 v150, v145, v145
	v_fmac_f32_e32 v150, v144, v144
	v_add_f32_e32 v135, v150, v135
	v_mul_f32_e32 v150, v147, v147
	v_fmac_f32_e32 v150, v146, v146
	v_add_f32_e32 v135, v150, v135
	s_nop 1
	v_add_f32_dpp v135, v135, v135 quad_perm:[1,0,3,2] row_mask:0xf bank_mask:0xf bound_ctrl:1
	s_nop 1
	v_add_f32_dpp v135, v135, v135 quad_perm:[2,3,0,1] row_mask:0xf bank_mask:0xf bound_ctrl:1
	s_nop 1
	v_add_f32_dpp v135, v135, v135 row_half_mirror row_mask:0xf bank_mask:0xf bound_ctrl:1
	s_nop 1
	v_add_f32_dpp v135, v135, v135 row_mirror row_mask:0xf bank_mask:0xf bound_ctrl:1
	v_mov_b32_e32 v150, v135
	s_nop 1
	v_permlane16_swap_b32_e32 v135, v150
	v_add_f32_e32 v135, v135, v150
	v_mov_b32_e32 v150, v135
	s_nop 1
	v_permlane32_swap_b32_e32 v135, v150
	v_add_f32_e32 v135, v135, v150
	v_fmamk_f32 v135, v135, 0x3b000000, v109
	v_rsq_f32_e32 v150, v135
	s_nop 0
	v_pk_mul_f32 v[136:137], v[140:141], v[150:151] op_sel_hi:[1,0]
	v_pk_mul_f32 v[140:141], v[144:145], v[150:151] op_sel_hi:[1,0]
	v_pk_fma_f32 v[136:137], v[8:9], v[136:137], v[12:13]
	v_pk_fma_f32 v[140:141], v[0:1], v[140:141], v[4:5]
	v_mul_f32_e32 v135, 0xbfb8aa3b, v136
	v_mul_f32_e32 v144, 0xbfb8aa3b, v140
	v_mul_f32_e32 v145, 0xbfb8aa3b, v137
	v_exp_f32_e32 v135, v135
	v_exp_f32_e32 v144, v144
	v_exp_f32_e32 v145, v145
	v_pk_mul_f32 v[138:139], v[142:143], v[150:151] op_sel_hi:[1,0]
	v_pk_mul_f32 v[142:143], v[146:147], v[150:151] op_sel_hi:[1,0]
	v_add_f32_e32 v135, 1.0, v135
	v_add_f32_e32 v144, 1.0, v144
	v_add_f32_e32 v145, 1.0, v145
	v_mul_f32_e32 v146, 0xbfb8aa3b, v141
	v_rcp_f32_e32 v135, v135
	v_rcp_f32_e32 v144, v144
	v_rcp_f32_e32 v145, v145
	v_exp_f32_e32 v146, v146
	v_pk_fma_f32 v[138:139], v[10:11], v[138:139], v[14:15]
	v_pk_fma_f32 v[142:143], v[2:3], v[142:143], v[6:7]
	v_mul_f32_e32 v135, v136, v135
	v_mul_f32_e32 v140, v140, v144
	v_mul_f32_e32 v136, v137, v145
	v_add_f32_e32 v137, 1.0, v146
	v_mul_f32_e32 v144, 0xbfb8aa3b, v138
	v_mul_f32_e32 v145, 0xbfb8aa3b, v142
	v_rcp_f32_e32 v137, v137
	v_exp_f32_e32 v144, v144
	v_exp_f32_e32 v145, v145
	v_mul_f32_e32 v146, 0xbfb8aa3b, v143
	v_mul_f32_e32 v141, v141, v137
	v_add_f32_e32 v137, 1.0, v144
	v_add_f32_e32 v144, 1.0, v145
	v_mul_f32_e32 v145, 0xbfb8aa3b, v139
	v_exp_f32_e32 v145, v145
	v_exp_f32_e32 v146, v146
	v_rcp_f32_e32 v137, v137
	v_rcp_f32_e32 v144, v144
	v_add_f32_e32 v145, 1.0, v145
	v_add_f32_e32 v146, 1.0, v146
	v_rcp_f32_e32 v145, v145
	v_rcp_f32_e32 v146, v146
	v_mul_f32_e32 v137, v138, v137
	v_mul_f32_e32 v142, v142, v144
	v_mul_f32_e32 v138, v139, v145
	v_mul_f32_e32 v139, v143, v146
	v_cvt_pk_bf16_f32 v136, v135, v136
	v_add_u32_e32 v135, s25, v101
	v_cvt_pk_bf16_f32 v137, v137, v138
	v_cvt_pk_bf16_f32 v138, v140, v141
	v_cvt_pk_bf16_f32 v139, v142, v139
	ds_read_b128 v[140:143], v135
	ds_read_b128 v[144:147], v135 offset:16
	global_store_dwordx4 v[148:149], v[136:139], off offset:1024
	v_lshl_add_u64 v[148:149], s[10:11], 0, v[80:81]
	v_add_co_u32_e32 v148, vcc, s28, v148
	s_waitcnt lgkmcnt(1)
	v_add_f32_e32 v135, v140, v141
	v_add_f32_e32 v150, v142, v143
	v_add_f32_e32 v135, v135, v150
	s_waitcnt lgkmcnt(0)
	v_add_f32_e32 v150, v144, v145
	v_add_f32_e32 v135, v135, v150
	v_add_f32_e32 v150, v146, v147
	v_add_f32_e32 v135, v150, v135
	v_addc_co_u32_e32 v149, vcc, 0, v149, vcc
	s_nop 0
	v_add_f32_dpp v135, v135, v135 quad_perm:[1,0,3,2] row_mask:0xf bank_mask:0xf bound_ctrl:1
	s_add_i32 s10, s8, s26
	s_ashr_i32 s11, s10, 31
	v_add_f32_dpp v135, v135, v135 quad_perm:[2,3,0,1] row_mask:0xf bank_mask:0xf bound_ctrl:1
	s_lshl_b64 s[10:11], s[10:11], 11
	s_add_u32 s10, s62, s10
	v_add_f32_dpp v135, v135, v135 row_half_mirror row_mask:0xf bank_mask:0xf bound_ctrl:1
	s_addc_u32 s11, s63, s11
	s_nop 0
	v_add_f32_dpp v135, v135, v135 row_mirror row_mask:0xf bank_mask:0xf bound_ctrl:1
	v_mov_b32_e32 v150, v135
	s_nop 1
	v_permlane16_swap_b32_e32 v135, v150
	v_add_f32_e32 v135, v135, v150
	v_mov_b32_e32 v150, v135
	s_nop 1
	v_permlane32_swap_b32_e32 v135, v150
	v_add_f32_e32 v135, v135, v150
	v_fmamk_f32 v143, v135, 0xbb000000, v143
	v_fmac_f32_e32 v141, 0xbb000000, v135
	v_fmamk_f32 v142, v135, 0xbb000000, v142
	v_fmamk_f32 v140, v135, 0xbb000000, v140
	v_fmamk_f32 v146, v135, 0xbb000000, v146
	v_fmamk_f32 v147, v135, 0xbb000000, v147
	v_fmamk_f32 v144, v135, 0xbb000000, v144
	v_fmac_f32_e32 v145, 0xbb000000, v135
	v_mul_f32_e32 v135, v141, v141
	v_mul_f32_e32 v150, v143, v143
	v_fmac_f32_e32 v135, v140, v140
	v_fmac_f32_e32 v150, v142, v142
	v_add_f32_e32 v135, v135, v150
	v_mul_f32_e32 v150, v145, v145
	v_fmac_f32_e32 v150, v144, v144
	v_add_f32_e32 v135, v150, v135
	v_mul_f32_e32 v150, v147, v147
	v_fmac_f32_e32 v150, v146, v146
	v_add_f32_e32 v135, v150, v135
	s_nop 1
	v_add_f32_dpp v135, v135, v135 quad_perm:[1,0,3,2] row_mask:0xf bank_mask:0xf bound_ctrl:1
	s_nop 1
	v_add_f32_dpp v135, v135, v135 quad_perm:[2,3,0,1] row_mask:0xf bank_mask:0xf bound_ctrl:1
	s_nop 1
	v_add_f32_dpp v135, v135, v135 row_half_mirror row_mask:0xf bank_mask:0xf bound_ctrl:1
	s_nop 1
	v_add_f32_dpp v135, v135, v135 row_mirror row_mask:0xf bank_mask:0xf bound_ctrl:1
	v_mov_b32_e32 v150, v135
	s_nop 1
	v_permlane16_swap_b32_e32 v135, v150
	v_add_f32_e32 v135, v135, v150
	v_mov_b32_e32 v150, v135
	s_nop 1
	v_permlane32_swap_b32_e32 v135, v150
	v_add_f32_e32 v135, v135, v150
	v_fmamk_f32 v135, v135, 0x3b000000, v109
	v_rsq_f32_e32 v150, v135
	s_nop 0
	v_pk_mul_f32 v[136:137], v[140:141], v[150:151] op_sel_hi:[1,0]
	v_pk_mul_f32 v[140:141], v[144:145], v[150:151] op_sel_hi:[1,0]
	v_pk_fma_f32 v[136:137], v[8:9], v[136:137], v[12:13]
	v_pk_fma_f32 v[140:141], v[0:1], v[140:141], v[4:5]
	v_mul_f32_e32 v135, 0xbfb8aa3b, v136
	v_mul_f32_e32 v144, 0xbfb8aa3b, v140
	v_mul_f32_e32 v145, 0xbfb8aa3b, v137
	v_exp_f32_e32 v135, v135
	v_exp_f32_e32 v144, v144
	v_exp_f32_e32 v145, v145
	v_pk_mul_f32 v[138:139], v[142:143], v[150:151] op_sel_hi:[1,0]
	v_pk_mul_f32 v[142:143], v[146:147], v[150:151] op_sel_hi:[1,0]
	v_add_f32_e32 v135, 1.0, v135
	v_add_f32_e32 v144, 1.0, v144
	v_add_f32_e32 v145, 1.0, v145
	v_mul_f32_e32 v146, 0xbfb8aa3b, v141
	v_rcp_f32_e32 v135, v135
	v_rcp_f32_e32 v144, v144
	v_rcp_f32_e32 v145, v145
	v_exp_f32_e32 v146, v146
	v_pk_fma_f32 v[138:139], v[10:11], v[138:139], v[14:15]
	v_pk_fma_f32 v[142:143], v[2:3], v[142:143], v[6:7]
	v_mul_f32_e32 v135, v136, v135
	v_mul_f32_e32 v140, v140, v144
	v_mul_f32_e32 v136, v137, v145
	v_add_f32_e32 v137, 1.0, v146
	v_mul_f32_e32 v144, 0xbfb8aa3b, v138
	v_mul_f32_e32 v145, 0xbfb8aa3b, v142
	v_rcp_f32_e32 v137, v137
	v_exp_f32_e32 v144, v144
	v_exp_f32_e32 v145, v145
	v_mul_f32_e32 v146, 0xbfb8aa3b, v143
	v_mul_f32_e32 v141, v141, v137
	v_add_f32_e32 v137, 1.0, v144
	v_add_f32_e32 v144, 1.0, v145
	v_mul_f32_e32 v145, 0xbfb8aa3b, v139
	v_exp_f32_e32 v145, v145
	v_exp_f32_e32 v146, v146
	v_rcp_f32_e32 v137, v137
	v_rcp_f32_e32 v144, v144
	v_add_f32_e32 v145, 1.0, v145
	v_add_f32_e32 v146, 1.0, v146
	v_rcp_f32_e32 v145, v145
	v_rcp_f32_e32 v146, v146
	v_mul_f32_e32 v137, v138, v137
	v_mul_f32_e32 v142, v142, v144
	v_mul_f32_e32 v138, v139, v145
	v_mul_f32_e32 v139, v143, v146
	v_cvt_pk_bf16_f32 v136, v135, v136
	v_add_u32_e32 v135, s27, v101
	v_cvt_pk_bf16_f32 v137, v137, v138
	v_cvt_pk_bf16_f32 v138, v140, v141
	v_cvt_pk_bf16_f32 v139, v142, v139
	ds_read_b128 v[140:143], v135
	ds_read_b128 v[144:147], v135 offset:16
	global_store_dwordx4 v[148:149], v[136:139], off offset:1024
	s_waitcnt lgkmcnt(1)
	v_add_f32_e32 v135, v140, v141
	v_add_f32_e32 v150, v142, v143
	v_add_f32_e32 v135, v135, v150
	s_waitcnt lgkmcnt(0)
	v_add_f32_e32 v150, v144, v145
	v_add_f32_e32 v135, v135, v150
	v_add_f32_e32 v150, v146, v147
	v_add_f32_e32 v135, v150, v135
	s_nop 1
	v_add_f32_dpp v135, v135, v135 quad_perm:[1,0,3,2] row_mask:0xf bank_mask:0xf bound_ctrl:1
	s_nop 1
	v_add_f32_dpp v135, v135, v135 quad_perm:[2,3,0,1] row_mask:0xf bank_mask:0xf bound_ctrl:1
	s_nop 1
	v_add_f32_dpp v135, v135, v135 row_half_mirror row_mask:0xf bank_mask:0xf bound_ctrl:1
	s_nop 1
	v_add_f32_dpp v135, v135, v135 row_mirror row_mask:0xf bank_mask:0xf bound_ctrl:1
	v_mov_b32_e32 v150, v135
	s_nop 1
	v_permlane16_swap_b32_e32 v135, v150
	v_add_f32_e32 v135, v135, v150
	v_mov_b32_e32 v150, v135
	s_nop 1
	v_permlane32_swap_b32_e32 v135, v150
	v_add_f32_e32 v135, v135, v150
	v_fmamk_f32 v143, v135, 0xbb000000, v143
	v_fmac_f32_e32 v141, 0xbb000000, v135
	v_fmamk_f32 v142, v135, 0xbb000000, v142
	v_fmamk_f32 v140, v135, 0xbb000000, v140
	v_fmamk_f32 v146, v135, 0xbb000000, v146
	v_fmamk_f32 v147, v135, 0xbb000000, v147
	v_fmamk_f32 v144, v135, 0xbb000000, v144
	v_fmac_f32_e32 v145, 0xbb000000, v135
	v_mul_f32_e32 v135, v141, v141
	v_mul_f32_e32 v150, v143, v143
	v_fmac_f32_e32 v135, v140, v140
	v_fmac_f32_e32 v150, v142, v142
	v_add_f32_e32 v135, v135, v150
	v_mul_f32_e32 v150, v145, v145
	v_fmac_f32_e32 v150, v144, v144
	v_add_f32_e32 v135, v150, v135
	v_mul_f32_e32 v150, v147, v147
	v_fmac_f32_e32 v150, v146, v146
	v_add_f32_e32 v135, v150, v135
	s_nop 1
	v_add_f32_dpp v135, v135, v135 quad_perm:[1,0,3,2] row_mask:0xf bank_mask:0xf bound_ctrl:1
	s_nop 1
	v_add_f32_dpp v135, v135, v135 quad_perm:[2,3,0,1] row_mask:0xf bank_mask:0xf bound_ctrl:1
	s_nop 1
	v_add_f32_dpp v135, v135, v135 row_half_mirror row_mask:0xf bank_mask:0xf bound_ctrl:1
	s_nop 1
	v_add_f32_dpp v135, v135, v135 row_mirror row_mask:0xf bank_mask:0xf bound_ctrl:1
	v_mov_b32_e32 v150, v135
	s_nop 1
	v_permlane16_swap_b32_e32 v135, v150
	v_add_f32_e32 v135, v135, v150
	v_mov_b32_e32 v150, v135
	s_nop 1
	v_permlane32_swap_b32_e32 v135, v150
	v_add_f32_e32 v135, v135, v150
	v_fmamk_f32 v135, v135, 0x3b000000, v109
	v_rsq_f32_e32 v150, v135
	s_nop 0
	v_pk_mul_f32 v[136:137], v[140:141], v[150:151] op_sel_hi:[1,0]
	v_pk_mul_f32 v[140:141], v[144:145], v[150:151] op_sel_hi:[1,0]
	v_pk_fma_f32 v[136:137], v[8:9], v[136:137], v[12:13]
	v_pk_fma_f32 v[140:141], v[0:1], v[140:141], v[4:5]
	v_mul_f32_e32 v135, 0xbfb8aa3b, v136
	v_mul_f32_e32 v144, 0xbfb8aa3b, v140
	v_mul_f32_e32 v145, 0xbfb8aa3b, v137
	v_exp_f32_e32 v135, v135
	v_exp_f32_e32 v144, v144
	v_exp_f32_e32 v145, v145
	v_pk_mul_f32 v[138:139], v[142:143], v[150:151] op_sel_hi:[1,0]
	v_pk_mul_f32 v[142:143], v[146:147], v[150:151] op_sel_hi:[1,0]
	v_add_f32_e32 v135, 1.0, v135
	v_add_f32_e32 v144, 1.0, v144
	v_add_f32_e32 v145, 1.0, v145
	v_mul_f32_e32 v146, 0xbfb8aa3b, v141
	v_rcp_f32_e32 v135, v135
	v_rcp_f32_e32 v144, v144
	v_rcp_f32_e32 v145, v145
	v_exp_f32_e32 v146, v146
	v_pk_fma_f32 v[138:139], v[10:11], v[138:139], v[14:15]
	v_pk_fma_f32 v[142:143], v[2:3], v[142:143], v[6:7]
	v_mul_f32_e32 v135, v136, v135
	v_mul_f32_e32 v140, v140, v144
	v_mul_f32_e32 v136, v137, v145
	v_add_f32_e32 v137, 1.0, v146
	v_mul_f32_e32 v144, 0xbfb8aa3b, v138
	v_mul_f32_e32 v145, 0xbfb8aa3b, v142
	v_rcp_f32_e32 v137, v137
	v_exp_f32_e32 v144, v144
	v_exp_f32_e32 v145, v145
	v_mul_f32_e32 v146, 0xbfb8aa3b, v143
	v_mul_f32_e32 v141, v141, v137
	v_add_f32_e32 v137, 1.0, v144
	v_add_f32_e32 v144, 1.0, v145
	v_mul_f32_e32 v145, 0xbfb8aa3b, v139
	v_exp_f32_e32 v145, v145
	v_exp_f32_e32 v146, v146
	v_rcp_f32_e32 v137, v137
	v_rcp_f32_e32 v144, v144
	v_add_f32_e32 v145, 1.0, v145
	v_rcp_f32_e32 v145, v145
	v_add_f32_e32 v146, 1.0, v146
	v_rcp_f32_e32 v146, v146
	v_mul_f32_e32 v137, v138, v137
	v_mul_f32_e32 v138, v139, v145
	v_cvt_pk_bf16_f32 v136, v135, v136
	v_cvt_pk_bf16_f32 v137, v137, v138
	v_cvt_pk_bf16_f32 v138, v140, v141
	v_lshl_add_u64 v[140:141], s[10:11], 0, v[80:81]
	v_add_co_u32_e32 v140, vcc, 0x5c00000, v140
	v_mul_f32_e32 v139, v143, v146
	s_nop 0
	v_addc_co_u32_e32 v141, vcc, 0, v141, vcc
	s_andn2_b64 vcc, exec, s[0:1]
	v_mul_f32_e32 v142, v142, v144
	v_cvt_pk_bf16_f32 v139, v142, v139
	global_store_dwordx4 v[140:141], v[136:139], off offset:1024
	s_barrier
	s_cbranch_vccz .LBB0_498
.LBB0_492:
	s_and_saveexec_b64 s[98:99], s[4:5]
	s_cbranch_execz .LBB0_496
	v_mov_b32_e32 v230, 1
	global_atomic_add v230, v81, v230, s[62:63] offset:128 sc0
.LBB0_496:
	s_or_b64 exec, exec, s[98:99]
	s_lshl_b32 s8, s29, 6
	s_add_i32 s0, s8, s3
	s_ashr_i32 s1, s0, 13
	s_mulk_i32 s1, 0x2040
	s_and_b32 s0, s0, 0x1fe0
	s_add_i32 s0, s0, s1
	s_add_i32 s0, s0, 50
	s_ashr_i32 s1, s0, 31
	s_lshl_b64 s[0:1], s[0:1], 10
	v_lshl_add_u64 v[136:137], v[82:83], 0, s[0:1]
	v_add_co_u32_e32 v138, vcc, 0x1000, v136
	s_waitcnt vmcnt(5)
	v_lshlrev_b32_e32 v184, 16, v105
	v_addc_co_u32_e32 v139, vcc, 0, v137, vcc
	global_load_dword v179, v[136:137], off
	global_load_dword v178, v[136:137], off offset:1024
	global_load_dword v177, v[136:137], off offset:2048
	global_load_dword v176, v[136:137], off offset:3072
	global_load_dword v175, v[138:139], off
	global_load_dword v174, v[138:139], off offset:1024
	global_load_dword v173, v[138:139], off offset:2048
	global_load_dword v171, v[138:139], off offset:3072
	v_add_co_u32_e32 v138, vcc, 0x2000, v136
	v_and_b32_e32 v185, 0xffff0000, v105
	s_nop 0
	v_addc_co_u32_e32 v139, vcc, 0, v137, vcc
	v_add_co_u32_e32 v140, vcc, 0x3000, v136
	s_waitcnt vmcnt(12)
	v_lshlrev_b32_e32 v186, 16, v106
	v_addc_co_u32_e32 v141, vcc, 0, v137, vcc
	global_load_dword v172, v[138:139], off
	global_load_dword v170, v[138:139], off offset:1024
	global_load_dword v169, v[138:139], off offset:2048
	global_load_dword v168, v[138:139], off offset:3072
	global_load_dword v167, v[140:141], off
	global_load_dword v166, v[140:141], off offset:1024
	global_load_dword v165, v[140:141], off offset:2048
	global_load_dword v164, v[140:141], off offset:3072
	v_add_co_u32_e32 v138, vcc, 0x4000, v136
	v_and_b32_e32 v187, 0xffff0000, v106
	s_nop 0
	v_addc_co_u32_e32 v139, vcc, 0, v137, vcc
	v_add_co_u32_e32 v140, vcc, 0x5000, v136
	s_waitcnt vmcnt(19)
	v_lshlrev_b32_e32 v188, 16, v107
	v_addc_co_u32_e32 v141, vcc, 0, v137, vcc
	global_load_dword v163, v[138:139], off
	global_load_dword v162, v[138:139], off offset:1024
	global_load_dword v161, v[138:139], off offset:2048
	global_load_dword v160, v[138:139], off offset:3072
	global_load_dword v159, v[140:141], off
	global_load_dword v158, v[140:141], off offset:1024
	global_load_dword v157, v[140:141], off offset:2048
	global_load_dword v156, v[140:141], off offset:3072
	v_add_co_u32_e32 v138, vcc, 0x6000, v136
	v_and_b32_e32 v189, 0xffff0000, v107
	s_nop 0
	v_addc_co_u32_e32 v139, vcc, 0, v137, vcc
	v_add_co_u32_e32 v140, vcc, 0x7000, v136
	v_lshlrev_b32_e32 v190, 16, v85
	s_nop 0
	v_addc_co_u32_e32 v141, vcc, 0, v137, vcc
	global_load_dword v155, v[138:139], off
	global_load_dword v154, v[138:139], off offset:1024
	global_load_dword v153, v[138:139], off offset:2048
	global_load_dword v152, v[138:139], off offset:3072
	global_load_dword v151, v[140:141], off
	global_load_dword v150, v[140:141], off offset:1024
	global_load_dword v149, v[140:141], off offset:2048
	global_load_dword v148, v[140:141], off offset:3072
	v_add_co_u32_e32 v138, vcc, 0x8000, v136
	v_and_b32_e32 v191, 0xffff0000, v85
	s_nop 0
	v_addc_co_u32_e32 v139, vcc, 0, v137, vcc
	v_add_co_u32_e32 v180, vcc, 0x9000, v136
	v_lshlrev_b32_e32 v192, 16, v86
	s_nop 0
	v_addc_co_u32_e32 v181, vcc, 0, v137, vcc
	global_load_dword v147, v[138:139], off
	global_load_dword v146, v[138:139], off offset:1024
	global_load_dword v145, v[138:139], off offset:2048
	global_load_dword v144, v[138:139], off offset:3072
	global_load_dword v143, v[180:181], off
	global_load_dword v142, v[180:181], off offset:1024
	global_load_dword v141, v[180:181], off offset:2048
	s_nop 0
	global_load_dword v139, v[180:181], off offset:3072
	v_add_co_u32_e32 v180, vcc, 0xa000, v136
	v_and_b32_e32 v193, 0xffff0000, v86
	s_nop 0
	v_addc_co_u32_e32 v181, vcc, 0, v137, vcc
	v_add_co_u32_e32 v182, vcc, 0xb000, v136
	v_lshlrev_b32_e32 v194, 16, v87
	s_nop 0
	v_addc_co_u32_e32 v183, vcc, 0, v137, vcc
	global_load_dword v140, v[180:181], off
	global_load_dword v138, v[180:181], off offset:1024
	global_load_dword v137, v[180:181], off offset:2048
	global_load_dword v136, v[180:181], off offset:3072
	global_load_dword v135, v[182:183], off
	global_load_dword v80, v[182:183], off offset:1024
	v_lshlrev_b32_e32 v180, 16, v103
	v_and_b32_e32 v181, 0xffff0000, v103
	v_pk_fma_f32 v[180:181], v[72:73], v[180:181], v[78:79]
	v_lshlrev_b32_e32 v182, 16, v104
	v_and_b32_e32 v183, 0xffff0000, v104
	v_pk_fma_f32 v[180:181], v[74:75], v[182:183], v[180:181]
	v_pk_fma_f32 v[182:183], v[72:73], v[182:183], v[78:79]
	v_pk_fma_f32 v[180:181], v[76:77], v[184:185], v[180:181]
	v_pk_fma_f32 v[182:183], v[74:75], v[184:185], v[182:183]
	v_pk_fma_f32 v[184:185], v[72:73], v[184:185], v[78:79]
	v_pk_fma_f32 v[180:181], v[32:33], v[186:187], v[180:181]
	v_pk_fma_f32 v[182:183], v[76:77], v[186:187], v[182:183]
	v_pk_fma_f32 v[184:185], v[74:75], v[186:187], v[184:185]
	v_pk_fma_f32 v[186:187], v[72:73], v[186:187], v[78:79]
	v_pk_fma_f32 v[180:181], v[16:17], v[188:189], v[180:181]
	v_pk_fma_f32 v[182:183], v[32:33], v[188:189], v[182:183]
	v_pk_fma_f32 v[184:185], v[76:77], v[188:189], v[184:185]
	v_pk_fma_f32 v[186:187], v[74:75], v[188:189], v[186:187]
	v_pk_fma_f32 v[188:189], v[72:73], v[188:189], v[78:79]
	v_pk_fma_f32 v[180:181], v[18:19], v[190:191], v[180:181]
	v_pk_fma_f32 v[182:183], v[16:17], v[190:191], v[182:183]
	v_pk_fma_f32 v[184:185], v[32:33], v[190:191], v[184:185]
	v_pk_fma_f32 v[186:187], v[76:77], v[190:191], v[186:187]
	v_pk_fma_f32 v[188:189], v[74:75], v[190:191], v[188:189]
	v_pk_fma_f32 v[190:191], v[72:73], v[190:191], v[78:79]
	v_pk_fma_f32 v[180:181], v[20:21], v[192:193], v[180:181]
	v_pk_fma_f32 v[182:183], v[18:19], v[192:193], v[182:183]
	v_pk_fma_f32 v[184:185], v[16:17], v[192:193], v[184:185]
	v_pk_fma_f32 v[186:187], v[32:33], v[192:193], v[186:187]
	v_pk_fma_f32 v[188:189], v[76:77], v[192:193], v[188:189]
	v_pk_fma_f32 v[190:191], v[74:75], v[192:193], v[190:191]
	v_pk_fma_f32 v[192:193], v[72:73], v[192:193], v[78:79]
	v_and_b32_e32 v195, 0xffff0000, v87
	v_pk_fma_f32 v[180:181], v[34:35], v[194:195], v[180:181]
	v_pk_fma_f32 v[182:183], v[20:21], v[194:195], v[182:183]
	v_pk_fma_f32 v[184:185], v[18:19], v[194:195], v[184:185]
	v_pk_fma_f32 v[186:187], v[16:17], v[194:195], v[186:187]
	v_pk_fma_f32 v[188:189], v[32:33], v[194:195], v[188:189]
	v_pk_fma_f32 v[190:191], v[76:77], v[194:195], v[190:191]
	v_pk_fma_f32 v[192:193], v[74:75], v[194:195], v[192:193]
	v_pk_fma_f32 v[194:195], v[72:73], v[194:195], v[78:79]
	s_waitcnt vmcnt(48)
	v_lshlrev_b32_e32 v196, 16, v114
	v_and_b32_e32 v197, 0xffff0000, v114
	v_pk_fma_f32 v[180:181], v[22:23], v[196:197], v[180:181]
	v_pk_fma_f32 v[182:183], v[34:35], v[196:197], v[182:183]
	v_pk_fma_f32 v[184:185], v[20:21], v[196:197], v[184:185]
	v_pk_fma_f32 v[186:187], v[18:19], v[196:197], v[186:187]
	v_pk_fma_f32 v[188:189], v[16:17], v[196:197], v[188:189]
	v_pk_fma_f32 v[190:191], v[32:33], v[196:197], v[190:191]
	v_pk_fma_f32 v[192:193], v[76:77], v[196:197], v[192:193]
	v_pk_fma_f32 v[194:195], v[74:75], v[196:197], v[194:195]
	v_pk_fma_f32 v[196:197], v[72:73], v[196:197], v[78:79]
	s_waitcnt vmcnt(47)
	v_lshlrev_b32_e32 v198, 16, v115
	v_and_b32_e32 v199, 0xffff0000, v115
	v_pk_fma_f32 v[180:181], v[24:25], v[198:199], v[180:181]
	v_pk_fma_f32 v[182:183], v[22:23], v[198:199], v[182:183]
	v_pk_fma_f32 v[184:185], v[34:35], v[198:199], v[184:185]
	v_pk_fma_f32 v[186:187], v[20:21], v[198:199], v[186:187]
	v_pk_fma_f32 v[188:189], v[18:19], v[198:199], v[188:189]
	v_pk_fma_f32 v[190:191], v[16:17], v[198:199], v[190:191]
	v_pk_fma_f32 v[192:193], v[32:33], v[198:199], v[192:193]
	v_pk_fma_f32 v[194:195], v[76:77], v[198:199], v[194:195]
	v_pk_fma_f32 v[196:197], v[74:75], v[198:199], v[196:197]
	v_pk_fma_f32 v[198:199], v[72:73], v[198:199], v[78:79]
	v_lshlrev_b32_e32 v200, 16, v88
	v_and_b32_e32 v201, 0xffff0000, v88
	v_pk_fma_f32 v[180:181], v[26:27], v[200:201], v[180:181]
	v_pk_fma_f32 v[182:183], v[24:25], v[200:201], v[182:183]
	v_pk_fma_f32 v[184:185], v[22:23], v[200:201], v[184:185]
	v_pk_fma_f32 v[186:187], v[34:35], v[200:201], v[186:187]
	v_pk_fma_f32 v[188:189], v[20:21], v[200:201], v[188:189]
	v_pk_fma_f32 v[190:191], v[18:19], v[200:201], v[190:191]
	v_pk_fma_f32 v[192:193], v[16:17], v[200:201], v[192:193]
	v_pk_fma_f32 v[194:195], v[32:33], v[200:201], v[194:195]
	v_pk_fma_f32 v[196:197], v[76:77], v[200:201], v[196:197]
	v_pk_fma_f32 v[198:199], v[74:75], v[200:201], v[198:199]
	v_pk_fma_f32 v[200:201], v[72:73], v[200:201], v[78:79]
	v_lshlrev_b32_e32 v202, 16, v89
	v_and_b32_e32 v203, 0xffff0000, v89
	v_pk_fma_f32 v[180:181], v[36:37], v[202:203], v[180:181]
	v_pk_fma_f32 v[182:183], v[26:27], v[202:203], v[182:183]
	v_pk_fma_f32 v[184:185], v[24:25], v[202:203], v[184:185]
	v_pk_fma_f32 v[186:187], v[22:23], v[202:203], v[186:187]
	v_pk_fma_f32 v[188:189], v[34:35], v[202:203], v[188:189]
	v_pk_fma_f32 v[190:191], v[20:21], v[202:203], v[190:191]
	v_pk_fma_f32 v[192:193], v[18:19], v[202:203], v[192:193]
	v_pk_fma_f32 v[194:195], v[16:17], v[202:203], v[194:195]
	v_pk_fma_f32 v[196:197], v[32:33], v[202:203], v[196:197]
	v_pk_fma_f32 v[198:199], v[76:77], v[202:203], v[198:199]
	v_pk_fma_f32 v[200:201], v[74:75], v[202:203], v[200:201]
	v_pk_fma_f32 v[202:203], v[72:73], v[202:203], v[78:79]
	v_lshlrev_b32_e32 v204, 16, v90
	v_and_b32_e32 v205, 0xffff0000, v90
	v_pk_fma_f32 v[180:181], v[28:29], v[204:205], v[180:181]
	v_pk_fma_f32 v[182:183], v[36:37], v[204:205], v[182:183]
	v_pk_fma_f32 v[184:185], v[26:27], v[204:205], v[184:185]
	v_pk_fma_f32 v[186:187], v[24:25], v[204:205], v[186:187]
	v_pk_fma_f32 v[188:189], v[22:23], v[204:205], v[188:189]
	v_pk_fma_f32 v[190:191], v[34:35], v[204:205], v[190:191]
	v_pk_fma_f32 v[192:193], v[20:21], v[204:205], v[192:193]
	v_pk_fma_f32 v[194:195], v[18:19], v[204:205], v[194:195]
	v_pk_fma_f32 v[196:197], v[16:17], v[204:205], v[196:197]
	v_pk_fma_f32 v[198:199], v[32:33], v[204:205], v[198:199]
	v_pk_fma_f32 v[200:201], v[76:77], v[204:205], v[200:201]
	v_pk_fma_f32 v[202:203], v[74:75], v[204:205], v[202:203]
	v_pk_fma_f32 v[204:205], v[72:73], v[204:205], v[78:79]
	v_lshlrev_b32_e32 v206, 16, v91
	v_and_b32_e32 v207, 0xffff0000, v91
	v_pk_fma_f32 v[180:181], v[30:31], v[206:207], v[180:181]
	v_pk_fma_f32 v[182:183], v[28:29], v[206:207], v[182:183]
	v_pk_fma_f32 v[184:185], v[36:37], v[206:207], v[184:185]
	v_pk_fma_f32 v[186:187], v[26:27], v[206:207], v[186:187]
	v_pk_fma_f32 v[188:189], v[24:25], v[206:207], v[188:189]
	v_pk_fma_f32 v[190:191], v[22:23], v[206:207], v[190:191]
	v_pk_fma_f32 v[192:193], v[34:35], v[206:207], v[192:193]
	v_pk_fma_f32 v[194:195], v[20:21], v[206:207], v[194:195]
	v_pk_fma_f32 v[196:197], v[18:19], v[206:207], v[196:197]
	v_pk_fma_f32 v[198:199], v[16:17], v[206:207], v[198:199]
	v_pk_fma_f32 v[200:201], v[32:33], v[206:207], v[200:201]
	v_pk_fma_f32 v[202:203], v[76:77], v[206:207], v[202:203]
	v_pk_fma_f32 v[204:205], v[74:75], v[206:207], v[204:205]
	v_pk_fma_f32 v[206:207], v[72:73], v[206:207], v[78:79]
	v_lshlrev_b32_e32 v208, 16, v92
	v_and_b32_e32 v209, 0xffff0000, v92
	v_pk_fma_f32 v[180:181], v[40:41], v[208:209], v[180:181]
	v_pk_fma_f32 v[182:183], v[30:31], v[208:209], v[182:183]
	v_pk_fma_f32 v[184:185], v[28:29], v[208:209], v[184:185]
	v_pk_fma_f32 v[186:187], v[36:37], v[208:209], v[186:187]
	v_pk_fma_f32 v[188:189], v[26:27], v[208:209], v[188:189]
	v_pk_fma_f32 v[190:191], v[24:25], v[208:209], v[190:191]
	v_pk_fma_f32 v[192:193], v[22:23], v[208:209], v[192:193]
	v_pk_fma_f32 v[194:195], v[34:35], v[208:209], v[194:195]
	v_pk_fma_f32 v[196:197], v[20:21], v[208:209], v[196:197]
	v_pk_fma_f32 v[198:199], v[18:19], v[208:209], v[198:199]
	v_pk_fma_f32 v[200:201], v[16:17], v[208:209], v[200:201]
	v_pk_fma_f32 v[202:203], v[32:33], v[208:209], v[202:203]
	v_pk_fma_f32 v[204:205], v[76:77], v[208:209], v[204:205]
	v_pk_fma_f32 v[206:207], v[74:75], v[208:209], v[206:207]
	v_pk_fma_f32 v[208:209], v[72:73], v[208:209], v[78:79]
	v_lshlrev_b32_e32 v210, 16, v93
	v_and_b32_e32 v211, 0xffff0000, v93
	v_pk_fma_f32 v[180:181], v[38:39], v[210:211], v[180:181]
	v_pk_fma_f32 v[182:183], v[40:41], v[210:211], v[182:183]
	v_pk_fma_f32 v[184:185], v[30:31], v[210:211], v[184:185]
	v_pk_fma_f32 v[186:187], v[28:29], v[210:211], v[186:187]
	v_pk_fma_f32 v[188:189], v[36:37], v[210:211], v[188:189]
	v_pk_fma_f32 v[190:191], v[26:27], v[210:211], v[190:191]
	v_pk_fma_f32 v[192:193], v[24:25], v[210:211], v[192:193]
	v_pk_fma_f32 v[194:195], v[22:23], v[210:211], v[194:195]
	v_pk_fma_f32 v[196:197], v[34:35], v[210:211], v[196:197]
	v_pk_fma_f32 v[198:199], v[20:21], v[210:211], v[198:199]
	v_pk_fma_f32 v[200:201], v[18:19], v[210:211], v[200:201]
	v_pk_fma_f32 v[202:203], v[16:17], v[210:211], v[202:203]
	v_pk_fma_f32 v[204:205], v[32:33], v[210:211], v[204:205]
	v_pk_fma_f32 v[206:207], v[76:77], v[210:211], v[206:207]
	v_pk_fma_f32 v[208:209], v[74:75], v[210:211], v[208:209]
	v_pk_fma_f32 v[210:211], v[72:73], v[210:211], v[78:79]
	v_lshlrev_b32_e32 v212, 16, v94
	v_and_b32_e32 v213, 0xffff0000, v94
	v_pk_fma_f32 v[180:181], v[42:43], v[212:213], v[180:181]
	v_pk_fma_f32 v[182:183], v[38:39], v[212:213], v[182:183]
	v_pk_fma_f32 v[184:185], v[40:41], v[212:213], v[184:185]
	v_pk_fma_f32 v[186:187], v[30:31], v[212:213], v[186:187]
	v_pk_fma_f32 v[188:189], v[28:29], v[212:213], v[188:189]
	v_pk_fma_f32 v[190:191], v[36:37], v[212:213], v[190:191]
	v_pk_fma_f32 v[192:193], v[26:27], v[212:213], v[192:193]
	v_pk_fma_f32 v[194:195], v[24:25], v[212:213], v[194:195]
	v_pk_fma_f32 v[196:197], v[22:23], v[212:213], v[196:197]
	v_pk_fma_f32 v[198:199], v[34:35], v[212:213], v[198:199]
	v_pk_fma_f32 v[200:201], v[20:21], v[212:213], v[200:201]
	v_pk_fma_f32 v[202:203], v[18:19], v[212:213], v[202:203]
	v_pk_fma_f32 v[204:205], v[16:17], v[212:213], v[204:205]
	v_pk_fma_f32 v[206:207], v[32:33], v[212:213], v[206:207]
	v_pk_fma_f32 v[208:209], v[76:77], v[212:213], v[208:209]
	v_pk_fma_f32 v[210:211], v[74:75], v[212:213], v[210:211]
	v_lshlrev_b32_e32 v212, 16, v95
	v_and_b32_e32 v213, 0xffff0000, v95
	v_pk_fma_f32 v[180:181], v[44:45], v[212:213], v[180:181]
	v_pk_fma_f32 v[182:183], v[42:43], v[212:213], v[182:183]
	v_pk_fma_f32 v[184:185], v[38:39], v[212:213], v[184:185]
	v_pk_fma_f32 v[186:187], v[40:41], v[212:213], v[186:187]
	v_pk_fma_f32 v[188:189], v[30:31], v[212:213], v[188:189]
	v_pk_fma_f32 v[190:191], v[28:29], v[212:213], v[190:191]
	v_pk_fma_f32 v[192:193], v[36:37], v[212:213], v[192:193]
	v_pk_fma_f32 v[194:195], v[26:27], v[212:213], v[194:195]
	v_pk_fma_f32 v[196:197], v[24:25], v[212:213], v[196:197]
	v_pk_fma_f32 v[198:199], v[22:23], v[212:213], v[198:199]
	v_pk_fma_f32 v[200:201], v[34:35], v[212:213], v[200:201]
	v_pk_fma_f32 v[202:203], v[20:21], v[212:213], v[202:203]
	v_pk_fma_f32 v[204:205], v[18:19], v[212:213], v[204:205]
	v_pk_fma_f32 v[206:207], v[16:17], v[212:213], v[206:207]
	v_pk_fma_f32 v[208:209], v[32:33], v[212:213], v[208:209]
	v_pk_fma_f32 v[210:211], v[76:77], v[212:213], v[210:211]
	v_lshlrev_b32_e32 v212, 16, v96
	v_and_b32_e32 v213, 0xffff0000, v96
	v_pk_fma_f32 v[180:181], v[46:47], v[212:213], v[180:181]
	v_pk_fma_f32 v[182:183], v[44:45], v[212:213], v[182:183]
	v_pk_fma_f32 v[184:185], v[42:43], v[212:213], v[184:185]
	v_pk_fma_f32 v[186:187], v[38:39], v[212:213], v[186:187]
	v_pk_fma_f32 v[188:189], v[40:41], v[212:213], v[188:189]
	v_pk_fma_f32 v[190:191], v[30:31], v[212:213], v[190:191]
	v_pk_fma_f32 v[192:193], v[28:29], v[212:213], v[192:193]
	v_pk_fma_f32 v[194:195], v[36:37], v[212:213], v[194:195]
	v_pk_fma_f32 v[196:197], v[26:27], v[212:213], v[196:197]
	v_pk_fma_f32 v[198:199], v[24:25], v[212:213], v[198:199]
	v_pk_fma_f32 v[200:201], v[22:23], v[212:213], v[200:201]
	v_pk_fma_f32 v[202:203], v[34:35], v[212:213], v[202:203]
	v_pk_fma_f32 v[204:205], v[20:21], v[212:213], v[204:205]
	v_pk_fma_f32 v[206:207], v[18:19], v[212:213], v[206:207]
	v_pk_fma_f32 v[208:209], v[16:17], v[212:213], v[208:209]
	v_pk_fma_f32 v[210:211], v[32:33], v[212:213], v[210:211]
	v_lshlrev_b32_e32 v212, 16, v97
	v_and_b32_e32 v213, 0xffff0000, v97
	v_pk_fma_f32 v[180:181], v[64:65], v[212:213], v[180:181]
	v_pk_fma_f32 v[182:183], v[46:47], v[212:213], v[182:183]
	v_pk_fma_f32 v[184:185], v[44:45], v[212:213], v[184:185]
	v_pk_fma_f32 v[186:187], v[42:43], v[212:213], v[186:187]
	v_pk_fma_f32 v[188:189], v[38:39], v[212:213], v[188:189]
	v_pk_fma_f32 v[190:191], v[40:41], v[212:213], v[190:191]
	v_pk_fma_f32 v[192:193], v[30:31], v[212:213], v[192:193]
	v_pk_fma_f32 v[194:195], v[28:29], v[212:213], v[194:195]
	v_pk_fma_f32 v[196:197], v[36:37], v[212:213], v[196:197]
	v_pk_fma_f32 v[198:199], v[26:27], v[212:213], v[198:199]
	v_pk_fma_f32 v[200:201], v[24:25], v[212:213], v[200:201]
	v_pk_fma_f32 v[202:203], v[22:23], v[212:213], v[202:203]
	v_pk_fma_f32 v[204:205], v[34:35], v[212:213], v[204:205]
	v_pk_fma_f32 v[206:207], v[20:21], v[212:213], v[206:207]
	v_pk_fma_f32 v[208:209], v[18:19], v[212:213], v[208:209]
	v_pk_fma_f32 v[210:211], v[16:17], v[212:213], v[210:211]
	v_lshlrev_b32_e32 v212, 16, v98
	v_and_b32_e32 v213, 0xffff0000, v98
	v_pk_fma_f32 v[180:181], v[48:49], v[212:213], v[180:181]
	v_pk_fma_f32 v[182:183], v[64:65], v[212:213], v[182:183]
	v_pk_fma_f32 v[184:185], v[46:47], v[212:213], v[184:185]
	v_pk_fma_f32 v[186:187], v[44:45], v[212:213], v[186:187]
	v_pk_fma_f32 v[188:189], v[42:43], v[212:213], v[188:189]
	v_pk_fma_f32 v[190:191], v[38:39], v[212:213], v[190:191]
	v_pk_fma_f32 v[192:193], v[40:41], v[212:213], v[192:193]
	v_pk_fma_f32 v[194:195], v[30:31], v[212:213], v[194:195]
	v_pk_fma_f32 v[196:197], v[28:29], v[212:213], v[196:197]
	v_pk_fma_f32 v[198:199], v[36:37], v[212:213], v[198:199]
	v_pk_fma_f32 v[200:201], v[26:27], v[212:213], v[200:201]
	v_pk_fma_f32 v[202:203], v[24:25], v[212:213], v[202:203]
	v_pk_fma_f32 v[204:205], v[22:23], v[212:213], v[204:205]
	v_pk_fma_f32 v[206:207], v[34:35], v[212:213], v[206:207]
	v_pk_fma_f32 v[208:209], v[20:21], v[212:213], v[208:209]
	v_pk_fma_f32 v[210:211], v[18:19], v[212:213], v[210:211]
	v_lshlrev_b32_e32 v212, 16, v99
	v_and_b32_e32 v213, 0xffff0000, v99
	v_pk_fma_f32 v[180:181], v[50:51], v[212:213], v[180:181]
	v_pk_fma_f32 v[182:183], v[48:49], v[212:213], v[182:183]
	v_pk_fma_f32 v[184:185], v[64:65], v[212:213], v[184:185]
	v_pk_fma_f32 v[186:187], v[46:47], v[212:213], v[186:187]
	v_pk_fma_f32 v[188:189], v[44:45], v[212:213], v[188:189]
	v_pk_fma_f32 v[190:191], v[42:43], v[212:213], v[190:191]
	v_pk_fma_f32 v[192:193], v[38:39], v[212:213], v[192:193]
	v_pk_fma_f32 v[194:195], v[40:41], v[212:213], v[194:195]
	v_pk_fma_f32 v[196:197], v[30:31], v[212:213], v[196:197]
	v_pk_fma_f32 v[198:199], v[28:29], v[212:213], v[198:199]
	v_pk_fma_f32 v[200:201], v[36:37], v[212:213], v[200:201]
	v_pk_fma_f32 v[202:203], v[26:27], v[212:213], v[202:203]
	v_pk_fma_f32 v[204:205], v[24:25], v[212:213], v[204:205]
	v_pk_fma_f32 v[206:207], v[22:23], v[212:213], v[206:207]
	v_pk_fma_f32 v[208:209], v[34:35], v[212:213], v[208:209]
	v_pk_fma_f32 v[210:211], v[20:21], v[212:213], v[210:211]
	v_lshlrev_b32_e32 v212, 16, v100
	v_and_b32_e32 v213, 0xffff0000, v100
	v_pk_fma_f32 v[180:181], v[52:53], v[212:213], v[180:181]
	v_pk_fma_f32 v[182:183], v[50:51], v[212:213], v[182:183]
	v_pk_fma_f32 v[184:185], v[48:49], v[212:213], v[184:185]
	v_pk_fma_f32 v[186:187], v[64:65], v[212:213], v[186:187]
	v_pk_fma_f32 v[188:189], v[46:47], v[212:213], v[188:189]
	v_pk_fma_f32 v[190:191], v[44:45], v[212:213], v[190:191]
	v_pk_fma_f32 v[192:193], v[42:43], v[212:213], v[192:193]
	v_pk_fma_f32 v[194:195], v[38:39], v[212:213], v[194:195]
	v_pk_fma_f32 v[196:197], v[40:41], v[212:213], v[196:197]
	v_pk_fma_f32 v[198:199], v[30:31], v[212:213], v[198:199]
	v_pk_fma_f32 v[200:201], v[28:29], v[212:213], v[200:201]
	v_pk_fma_f32 v[202:203], v[36:37], v[212:213], v[202:203]
	v_pk_fma_f32 v[204:205], v[26:27], v[212:213], v[204:205]
	v_pk_fma_f32 v[206:207], v[24:25], v[212:213], v[206:207]
	v_pk_fma_f32 v[208:209], v[22:23], v[212:213], v[208:209]
	v_pk_fma_f32 v[210:211], v[34:35], v[212:213], v[210:211]
	v_lshlrev_b32_e32 v212, 16, v117
	v_and_b32_e32 v213, 0xffff0000, v117
	v_pk_fma_f32 v[180:181], v[66:67], v[212:213], v[180:181]
	v_pk_fma_f32 v[182:183], v[52:53], v[212:213], v[182:183]
	v_pk_fma_f32 v[184:185], v[50:51], v[212:213], v[184:185]
	v_pk_fma_f32 v[186:187], v[48:49], v[212:213], v[186:187]
	v_pk_fma_f32 v[188:189], v[64:65], v[212:213], v[188:189]
	v_pk_fma_f32 v[190:191], v[46:47], v[212:213], v[190:191]
	v_pk_fma_f32 v[192:193], v[44:45], v[212:213], v[192:193]
	v_pk_fma_f32 v[194:195], v[42:43], v[212:213], v[194:195]
	v_pk_fma_f32 v[196:197], v[38:39], v[212:213], v[196:197]
	v_pk_fma_f32 v[198:199], v[40:41], v[212:213], v[198:199]
	v_pk_fma_f32 v[200:201], v[30:31], v[212:213], v[200:201]
	v_pk_fma_f32 v[202:203], v[28:29], v[212:213], v[202:203]
	v_pk_fma_f32 v[204:205], v[36:37], v[212:213], v[204:205]
	v_pk_fma_f32 v[206:207], v[26:27], v[212:213], v[206:207]
	v_pk_fma_f32 v[208:209], v[24:25], v[212:213], v[208:209]
	v_pk_fma_f32 v[210:211], v[22:23], v[212:213], v[210:211]
	v_lshlrev_b32_e32 v212, 16, v110
	v_and_b32_e32 v213, 0xffff0000, v110
	v_pk_fma_f32 v[180:181], v[54:55], v[212:213], v[180:181]
	v_pk_fma_f32 v[182:183], v[66:67], v[212:213], v[182:183]
	v_pk_fma_f32 v[184:185], v[52:53], v[212:213], v[184:185]
	v_pk_fma_f32 v[186:187], v[50:51], v[212:213], v[186:187]
	v_pk_fma_f32 v[188:189], v[48:49], v[212:213], v[188:189]
	v_pk_fma_f32 v[190:191], v[64:65], v[212:213], v[190:191]
	v_pk_fma_f32 v[192:193], v[46:47], v[212:213], v[192:193]
	v_pk_fma_f32 v[194:195], v[44:45], v[212:213], v[194:195]
	v_pk_fma_f32 v[196:197], v[42:43], v[212:213], v[196:197]
	v_pk_fma_f32 v[198:199], v[38:39], v[212:213], v[198:199]
	v_pk_fma_f32 v[200:201], v[40:41], v[212:213], v[200:201]
	v_pk_fma_f32 v[202:203], v[30:31], v[212:213], v[202:203]
	v_pk_fma_f32 v[204:205], v[28:29], v[212:213], v[204:205]
	v_pk_fma_f32 v[206:207], v[36:37], v[212:213], v[206:207]
	v_pk_fma_f32 v[208:209], v[26:27], v[212:213], v[208:209]
	v_pk_fma_f32 v[210:211], v[24:25], v[212:213], v[210:211]
	v_lshlrev_b32_e32 v212, 16, v111
	v_and_b32_e32 v213, 0xffff0000, v111
	v_pk_fma_f32 v[180:181], v[56:57], v[212:213], v[180:181]
	v_pk_fma_f32 v[182:183], v[54:55], v[212:213], v[182:183]
	v_pk_fma_f32 v[184:185], v[66:67], v[212:213], v[184:185]
	v_pk_fma_f32 v[186:187], v[52:53], v[212:213], v[186:187]
	v_pk_fma_f32 v[188:189], v[50:51], v[212:213], v[188:189]
	v_pk_fma_f32 v[190:191], v[48:49], v[212:213], v[190:191]
	v_pk_fma_f32 v[192:193], v[64:65], v[212:213], v[192:193]
	v_pk_fma_f32 v[194:195], v[46:47], v[212:213], v[194:195]
	v_pk_fma_f32 v[196:197], v[44:45], v[212:213], v[196:197]
	v_pk_fma_f32 v[198:199], v[42:43], v[212:213], v[198:199]
	v_pk_fma_f32 v[200:201], v[38:39], v[212:213], v[200:201]
	v_pk_fma_f32 v[202:203], v[40:41], v[212:213], v[202:203]
	v_pk_fma_f32 v[204:205], v[30:31], v[212:213], v[204:205]
	v_pk_fma_f32 v[206:207], v[28:29], v[212:213], v[206:207]
	v_pk_fma_f32 v[208:209], v[36:37], v[212:213], v[208:209]
	v_pk_fma_f32 v[210:211], v[26:27], v[212:213], v[210:211]
	v_lshlrev_b32_e32 v212, 16, v112
	v_and_b32_e32 v213, 0xffff0000, v112
	v_pk_fma_f32 v[180:181], v[58:59], v[212:213], v[180:181]
	v_pk_fma_f32 v[182:183], v[56:57], v[212:213], v[182:183]
	v_pk_fma_f32 v[184:185], v[54:55], v[212:213], v[184:185]
	v_pk_fma_f32 v[186:187], v[66:67], v[212:213], v[186:187]
	v_pk_fma_f32 v[188:189], v[52:53], v[212:213], v[188:189]
	v_pk_fma_f32 v[190:191], v[50:51], v[212:213], v[190:191]
	v_pk_fma_f32 v[192:193], v[48:49], v[212:213], v[192:193]
	v_pk_fma_f32 v[194:195], v[64:65], v[212:213], v[194:195]
	v_pk_fma_f32 v[196:197], v[46:47], v[212:213], v[196:197]
	v_pk_fma_f32 v[198:199], v[44:45], v[212:213], v[198:199]
	v_pk_fma_f32 v[200:201], v[42:43], v[212:213], v[200:201]
	v_pk_fma_f32 v[202:203], v[38:39], v[212:213], v[202:203]
	v_pk_fma_f32 v[204:205], v[40:41], v[212:213], v[204:205]
	v_pk_fma_f32 v[206:207], v[30:31], v[212:213], v[206:207]
	v_pk_fma_f32 v[208:209], v[28:29], v[212:213], v[208:209]
	v_pk_fma_f32 v[210:211], v[36:37], v[212:213], v[210:211]
	v_lshlrev_b32_e32 v212, 16, v113
	v_and_b32_e32 v213, 0xffff0000, v113
	v_pk_fma_f32 v[180:181], v[68:69], v[212:213], v[180:181]
	v_pk_fma_f32 v[182:183], v[58:59], v[212:213], v[182:183]
	v_pk_fma_f32 v[184:185], v[56:57], v[212:213], v[184:185]
	v_pk_fma_f32 v[186:187], v[54:55], v[212:213], v[186:187]
	v_pk_fma_f32 v[188:189], v[66:67], v[212:213], v[188:189]
	v_pk_fma_f32 v[190:191], v[52:53], v[212:213], v[190:191]
	v_pk_fma_f32 v[192:193], v[50:51], v[212:213], v[192:193]
	v_pk_fma_f32 v[194:195], v[48:49], v[212:213], v[194:195]
	v_pk_fma_f32 v[196:197], v[64:65], v[212:213], v[196:197]
	v_pk_fma_f32 v[198:199], v[46:47], v[212:213], v[198:199]
	v_pk_fma_f32 v[200:201], v[44:45], v[212:213], v[200:201]
	v_pk_fma_f32 v[202:203], v[42:43], v[212:213], v[202:203]
	v_pk_fma_f32 v[204:205], v[38:39], v[212:213], v[204:205]
	v_pk_fma_f32 v[206:207], v[40:41], v[212:213], v[206:207]
	v_pk_fma_f32 v[208:209], v[30:31], v[212:213], v[208:209]
	v_pk_fma_f32 v[210:211], v[28:29], v[212:213], v[210:211]
	v_lshlrev_b32_e32 v212, 16, v116
	v_and_b32_e32 v213, 0xffff0000, v116
	v_pk_fma_f32 v[180:181], v[60:61], v[212:213], v[180:181]
	v_pk_fma_f32 v[182:183], v[68:69], v[212:213], v[182:183]
	v_pk_fma_f32 v[184:185], v[58:59], v[212:213], v[184:185]
	v_pk_fma_f32 v[186:187], v[56:57], v[212:213], v[186:187]
	v_pk_fma_f32 v[188:189], v[54:55], v[212:213], v[188:189]
	v_pk_fma_f32 v[190:191], v[66:67], v[212:213], v[190:191]
	v_pk_fma_f32 v[192:193], v[52:53], v[212:213], v[192:193]
	v_pk_fma_f32 v[194:195], v[50:51], v[212:213], v[194:195]
	v_pk_fma_f32 v[196:197], v[48:49], v[212:213], v[196:197]
	v_pk_fma_f32 v[198:199], v[64:65], v[212:213], v[198:199]
	v_pk_fma_f32 v[200:201], v[46:47], v[212:213], v[200:201]
	v_pk_fma_f32 v[202:203], v[44:45], v[212:213], v[202:203]
	v_pk_fma_f32 v[204:205], v[42:43], v[212:213], v[204:205]
	v_pk_fma_f32 v[206:207], v[38:39], v[212:213], v[206:207]
	v_pk_fma_f32 v[208:209], v[40:41], v[212:213], v[208:209]
	v_pk_fma_f32 v[210:211], v[30:31], v[212:213], v[210:211]
	v_lshlrev_b32_e32 v212, 16, v121
	v_and_b32_e32 v213, 0xffff0000, v121
	v_pk_fma_f32 v[180:181], v[62:63], v[212:213], v[180:181]
	v_pk_fma_f32 v[182:183], v[60:61], v[212:213], v[182:183]
	v_pk_fma_f32 v[184:185], v[68:69], v[212:213], v[184:185]
	v_pk_fma_f32 v[186:187], v[58:59], v[212:213], v[186:187]
	v_pk_fma_f32 v[188:189], v[56:57], v[212:213], v[188:189]
	v_pk_fma_f32 v[190:191], v[54:55], v[212:213], v[190:191]
	v_pk_fma_f32 v[192:193], v[66:67], v[212:213], v[192:193]
	v_pk_fma_f32 v[194:195], v[52:53], v[212:213], v[194:195]
	v_pk_fma_f32 v[196:197], v[50:51], v[212:213], v[196:197]
	v_pk_fma_f32 v[198:199], v[48:49], v[212:213], v[198:199]
	v_pk_fma_f32 v[200:201], v[64:65], v[212:213], v[200:201]
	v_pk_fma_f32 v[202:203], v[46:47], v[212:213], v[202:203]
	v_pk_fma_f32 v[204:205], v[44:45], v[212:213], v[204:205]
	v_pk_fma_f32 v[206:207], v[42:43], v[212:213], v[206:207]
	v_pk_fma_f32 v[208:209], v[38:39], v[212:213], v[208:209]
	v_pk_fma_f32 v[210:211], v[40:41], v[212:213], v[210:211]
	v_lshlrev_b32_e32 v212, 16, v122
	v_and_b32_e32 v213, 0xffff0000, v122
	v_pk_fma_f32 v[180:181], v[70:71], v[212:213], v[180:181]
	v_pk_fma_f32 v[182:183], v[62:63], v[212:213], v[182:183]
	v_pk_fma_f32 v[184:185], v[60:61], v[212:213], v[184:185]
	v_pk_fma_f32 v[186:187], v[68:69], v[212:213], v[186:187]
	v_pk_fma_f32 v[188:189], v[58:59], v[212:213], v[188:189]
	v_pk_fma_f32 v[190:191], v[56:57], v[212:213], v[190:191]
	v_pk_fma_f32 v[192:193], v[54:55], v[212:213], v[192:193]
	v_pk_fma_f32 v[194:195], v[66:67], v[212:213], v[194:195]
	v_pk_fma_f32 v[196:197], v[52:53], v[212:213], v[196:197]
	v_pk_fma_f32 v[198:199], v[50:51], v[212:213], v[198:199]
	v_pk_fma_f32 v[200:201], v[48:49], v[212:213], v[200:201]
	v_pk_fma_f32 v[202:203], v[64:65], v[212:213], v[202:203]
	v_pk_fma_f32 v[204:205], v[46:47], v[212:213], v[204:205]
	v_pk_fma_f32 v[206:207], v[44:45], v[212:213], v[206:207]
	v_pk_fma_f32 v[208:209], v[42:43], v[212:213], v[208:209]
	v_pk_fma_f32 v[210:211], v[38:39], v[212:213], v[210:211]
	v_lshlrev_b32_e32 v212, 16, v124
	v_and_b32_e32 v213, 0xffff0000, v124
	v_pk_fma_f32 v[182:183], v[70:71], v[212:213], v[182:183]
	v_pk_fma_f32 v[184:185], v[62:63], v[212:213], v[184:185]
	v_pk_fma_f32 v[186:187], v[60:61], v[212:213], v[186:187]
	v_pk_fma_f32 v[188:189], v[68:69], v[212:213], v[188:189]
	v_pk_fma_f32 v[190:191], v[58:59], v[212:213], v[190:191]
	v_pk_fma_f32 v[192:193], v[56:57], v[212:213], v[192:193]
	v_pk_fma_f32 v[194:195], v[54:55], v[212:213], v[194:195]
	v_pk_fma_f32 v[196:197], v[66:67], v[212:213], v[196:197]
	v_pk_fma_f32 v[198:199], v[52:53], v[212:213], v[198:199]
	v_pk_fma_f32 v[200:201], v[50:51], v[212:213], v[200:201]
	v_pk_fma_f32 v[202:203], v[48:49], v[212:213], v[202:203]
	v_pk_fma_f32 v[204:205], v[64:65], v[212:213], v[204:205]
	v_pk_fma_f32 v[206:207], v[46:47], v[212:213], v[206:207]
	v_pk_fma_f32 v[208:209], v[44:45], v[212:213], v[208:209]
	v_pk_fma_f32 v[210:211], v[42:43], v[212:213], v[210:211]
	v_lshlrev_b32_e32 v212, 16, v118
	v_and_b32_e32 v213, 0xffff0000, v118
	v_pk_fma_f32 v[184:185], v[70:71], v[212:213], v[184:185]
	v_pk_fma_f32 v[186:187], v[62:63], v[212:213], v[186:187]
	v_pk_fma_f32 v[188:189], v[60:61], v[212:213], v[188:189]
	v_pk_fma_f32 v[190:191], v[68:69], v[212:213], v[190:191]
	v_pk_fma_f32 v[192:193], v[58:59], v[212:213], v[192:193]
	v_pk_fma_f32 v[194:195], v[56:57], v[212:213], v[194:195]
	v_pk_fma_f32 v[196:197], v[54:55], v[212:213], v[196:197]
	v_pk_fma_f32 v[198:199], v[66:67], v[212:213], v[198:199]
	v_pk_fma_f32 v[200:201], v[52:53], v[212:213], v[200:201]
	v_pk_fma_f32 v[202:203], v[50:51], v[212:213], v[202:203]
	v_pk_fma_f32 v[204:205], v[48:49], v[212:213], v[204:205]
	v_pk_fma_f32 v[206:207], v[64:65], v[212:213], v[206:207]
	v_pk_fma_f32 v[208:209], v[46:47], v[212:213], v[208:209]
	v_pk_fma_f32 v[210:211], v[44:45], v[212:213], v[210:211]
	v_lshlrev_b32_e32 v212, 16, v119
	v_and_b32_e32 v213, 0xffff0000, v119
	v_pk_fma_f32 v[186:187], v[70:71], v[212:213], v[186:187]
	v_pk_fma_f32 v[188:189], v[62:63], v[212:213], v[188:189]
	v_pk_fma_f32 v[190:191], v[60:61], v[212:213], v[190:191]
	v_pk_fma_f32 v[192:193], v[68:69], v[212:213], v[192:193]
	v_pk_fma_f32 v[194:195], v[58:59], v[212:213], v[194:195]
	v_pk_fma_f32 v[196:197], v[56:57], v[212:213], v[196:197]
	v_pk_fma_f32 v[198:199], v[54:55], v[212:213], v[198:199]
	v_pk_fma_f32 v[200:201], v[66:67], v[212:213], v[200:201]
	v_pk_fma_f32 v[202:203], v[52:53], v[212:213], v[202:203]
	v_pk_fma_f32 v[204:205], v[50:51], v[212:213], v[204:205]
	v_pk_fma_f32 v[206:207], v[48:49], v[212:213], v[206:207]
	v_pk_fma_f32 v[208:209], v[64:65], v[212:213], v[208:209]
	v_pk_fma_f32 v[210:211], v[46:47], v[212:213], v[210:211]
	v_lshlrev_b32_e32 v212, 16, v120
	v_and_b32_e32 v213, 0xffff0000, v120
	v_pk_fma_f32 v[188:189], v[70:71], v[212:213], v[188:189]
	v_pk_fma_f32 v[190:191], v[62:63], v[212:213], v[190:191]
	v_pk_fma_f32 v[192:193], v[60:61], v[212:213], v[192:193]
	v_pk_fma_f32 v[194:195], v[68:69], v[212:213], v[194:195]
	v_pk_fma_f32 v[196:197], v[58:59], v[212:213], v[196:197]
	v_pk_fma_f32 v[198:199], v[56:57], v[212:213], v[198:199]
	v_pk_fma_f32 v[200:201], v[54:55], v[212:213], v[200:201]
	v_pk_fma_f32 v[202:203], v[66:67], v[212:213], v[202:203]
	v_pk_fma_f32 v[204:205], v[52:53], v[212:213], v[204:205]
	v_pk_fma_f32 v[206:207], v[50:51], v[212:213], v[206:207]
	v_pk_fma_f32 v[208:209], v[48:49], v[212:213], v[208:209]
	v_pk_fma_f32 v[210:211], v[64:65], v[212:213], v[210:211]
	v_lshlrev_b32_e32 v212, 16, v123
	v_and_b32_e32 v213, 0xffff0000, v123
	v_pk_fma_f32 v[190:191], v[70:71], v[212:213], v[190:191]
	v_pk_fma_f32 v[192:193], v[62:63], v[212:213], v[192:193]
	v_pk_fma_f32 v[194:195], v[60:61], v[212:213], v[194:195]
	v_pk_fma_f32 v[196:197], v[68:69], v[212:213], v[196:197]
	v_pk_fma_f32 v[198:199], v[58:59], v[212:213], v[198:199]
	v_pk_fma_f32 v[200:201], v[56:57], v[212:213], v[200:201]
	v_pk_fma_f32 v[202:203], v[54:55], v[212:213], v[202:203]
	v_pk_fma_f32 v[204:205], v[66:67], v[212:213], v[204:205]
	v_pk_fma_f32 v[206:207], v[52:53], v[212:213], v[206:207]
	v_pk_fma_f32 v[208:209], v[50:51], v[212:213], v[208:209]
	v_pk_fma_f32 v[210:211], v[48:49], v[212:213], v[210:211]
	v_lshlrev_b32_e32 v212, 16, v125
	v_and_b32_e32 v213, 0xffff0000, v125
	v_pk_fma_f32 v[192:193], v[70:71], v[212:213], v[192:193]
	v_pk_fma_f32 v[194:195], v[62:63], v[212:213], v[194:195]
	v_pk_fma_f32 v[196:197], v[60:61], v[212:213], v[196:197]
	v_pk_fma_f32 v[198:199], v[68:69], v[212:213], v[198:199]
	v_pk_fma_f32 v[200:201], v[58:59], v[212:213], v[200:201]
	v_pk_fma_f32 v[202:203], v[56:57], v[212:213], v[202:203]
	v_pk_fma_f32 v[204:205], v[54:55], v[212:213], v[204:205]
	v_pk_fma_f32 v[206:207], v[66:67], v[212:213], v[206:207]
	v_pk_fma_f32 v[208:209], v[52:53], v[212:213], v[208:209]
	v_pk_fma_f32 v[210:211], v[50:51], v[212:213], v[210:211]
	v_lshlrev_b32_e32 v212, 16, v126
	v_and_b32_e32 v213, 0xffff0000, v126
	v_pk_fma_f32 v[194:195], v[70:71], v[212:213], v[194:195]
	v_pk_fma_f32 v[196:197], v[62:63], v[212:213], v[196:197]
	v_pk_fma_f32 v[198:199], v[60:61], v[212:213], v[198:199]
	v_pk_fma_f32 v[200:201], v[68:69], v[212:213], v[200:201]
	v_pk_fma_f32 v[202:203], v[58:59], v[212:213], v[202:203]
	v_pk_fma_f32 v[204:205], v[56:57], v[212:213], v[204:205]
	v_pk_fma_f32 v[206:207], v[54:55], v[212:213], v[206:207]
	v_pk_fma_f32 v[208:209], v[66:67], v[212:213], v[208:209]
	v_pk_fma_f32 v[210:211], v[52:53], v[212:213], v[210:211]
	v_lshlrev_b32_e32 v212, 16, v127
	v_and_b32_e32 v213, 0xffff0000, v127
	v_pk_fma_f32 v[196:197], v[70:71], v[212:213], v[196:197]
	v_pk_fma_f32 v[198:199], v[62:63], v[212:213], v[198:199]
	v_pk_fma_f32 v[200:201], v[60:61], v[212:213], v[200:201]
	v_pk_fma_f32 v[202:203], v[68:69], v[212:213], v[202:203]
	v_pk_fma_f32 v[204:205], v[58:59], v[212:213], v[204:205]
	v_pk_fma_f32 v[206:207], v[56:57], v[212:213], v[206:207]
	v_pk_fma_f32 v[208:209], v[54:55], v[212:213], v[208:209]
	v_pk_fma_f32 v[210:211], v[66:67], v[212:213], v[210:211]
	v_lshlrev_b32_e32 v212, 16, v129
	v_and_b32_e32 v213, 0xffff0000, v129
	v_pk_fma_f32 v[198:199], v[70:71], v[212:213], v[198:199]
	v_pk_fma_f32 v[200:201], v[62:63], v[212:213], v[200:201]
	v_pk_fma_f32 v[202:203], v[60:61], v[212:213], v[202:203]
	v_pk_fma_f32 v[204:205], v[68:69], v[212:213], v[204:205]
	v_pk_fma_f32 v[206:207], v[58:59], v[212:213], v[206:207]
	v_pk_fma_f32 v[208:209], v[56:57], v[212:213], v[208:209]
	v_pk_fma_f32 v[210:211], v[54:55], v[212:213], v[210:211]
	v_lshlrev_b32_e32 v212, 16, v128
	v_and_b32_e32 v213, 0xffff0000, v128
	v_pk_fma_f32 v[200:201], v[70:71], v[212:213], v[200:201]
	v_pk_fma_f32 v[202:203], v[62:63], v[212:213], v[202:203]
	v_pk_fma_f32 v[204:205], v[60:61], v[212:213], v[204:205]
	v_pk_fma_f32 v[206:207], v[68:69], v[212:213], v[206:207]
	v_pk_fma_f32 v[208:209], v[58:59], v[212:213], v[208:209]
	v_pk_fma_f32 v[210:211], v[56:57], v[212:213], v[210:211]
	v_lshlrev_b32_e32 v212, 16, v130
	v_and_b32_e32 v213, 0xffff0000, v130
	v_pk_fma_f32 v[202:203], v[70:71], v[212:213], v[202:203]
	v_pk_fma_f32 v[204:205], v[62:63], v[212:213], v[204:205]
	v_pk_fma_f32 v[206:207], v[60:61], v[212:213], v[206:207]
	v_pk_fma_f32 v[208:209], v[68:69], v[212:213], v[208:209]
	v_pk_fma_f32 v[210:211], v[58:59], v[212:213], v[210:211]
	v_lshlrev_b32_e32 v212, 16, v131
	v_and_b32_e32 v213, 0xffff0000, v131
	v_pk_fma_f32 v[204:205], v[70:71], v[212:213], v[204:205]
	v_pk_fma_f32 v[206:207], v[62:63], v[212:213], v[206:207]
	v_pk_fma_f32 v[208:209], v[60:61], v[212:213], v[208:209]
	v_pk_fma_f32 v[210:211], v[68:69], v[212:213], v[210:211]
	v_lshlrev_b32_e32 v212, 16, v132
	v_and_b32_e32 v213, 0xffff0000, v132
	s_cmpk_gt_i32 s2, 0x1ff
	v_pk_fma_f32 v[206:207], v[70:71], v[212:213], v[206:207]
	v_pk_fma_f32 v[208:209], v[62:63], v[212:213], v[208:209]
	v_pk_fma_f32 v[210:211], v[60:61], v[212:213], v[210:211]
	v_lshlrev_b32_e32 v212, 16, v133
	v_and_b32_e32 v213, 0xffff0000, v133
	s_cselect_b64 s[0:1], -1, 0
	v_pk_fma_f32 v[208:209], v[70:71], v[212:213], v[208:209]
	v_pk_fma_f32 v[210:211], v[62:63], v[212:213], v[210:211]
	s_waitcnt vmcnt(46)
	v_lshlrev_b32_e32 v212, 16, v134
	v_and_b32_e32 v213, 0xffff0000, v134
	s_and_b64 vcc, exec, s[0:1]
	v_pk_fma_f32 v[210:211], v[70:71], v[212:213], v[210:211]
	ds_write2st64_b64 v108, v[180:181], v[182:183] offset1:4
	ds_write2st64_b64 v108, v[184:185], v[186:187] offset0:8 offset1:12
	ds_write2st64_b64 v108, v[188:189], v[190:191] offset0:16 offset1:20
	ds_write2st64_b64 v108, v[192:193], v[194:195] offset0:24 offset1:28
	ds_write2st64_b64 v108, v[196:197], v[198:199] offset0:32 offset1:36
	ds_write2st64_b64 v108, v[200:201], v[202:203] offset0:40 offset1:44
	ds_write2st64_b64 v108, v[204:205], v[206:207] offset0:48 offset1:52
	ds_write2st64_b64 v108, v[208:209], v[210:211] offset0:56 offset1:60
	s_cbranch_vccnz .LBB0_491
	s_lshl_b32 s9, s2, 6
	s_add_i32 s9, s9, s3
	s_ashr_i32 s10, s9, 13
	s_mulk_i32 s10, 0x2040
	s_and_b32 s9, s9, 0x1fe0
	s_add_i32 s9, s9, s10
	s_add_i32 s10, s9, 34
	s_ashr_i32 s11, s10, 31
	s_lshl_b64 s[10:11], s[10:11], 10
	v_lshl_add_u64 v[130:131], v[82:83], 0, s[10:11]
	v_add_co_u32_e32 v88, vcc, 0x1000, v130
	s_nop 1
	v_addc_co_u32_e32 v89, vcc, 0, v131, vcc
	v_add_co_u32_e32 v90, vcc, 0x2000, v130
	global_load_dword v103, v[130:131], off
	global_load_dword v104, v[130:131], off offset:1024
	global_load_dword v105, v[130:131], off offset:2048
	global_load_dword v106, v[130:131], off offset:3072
	global_load_dword v107, v[88:89], off
	global_load_dword v85, v[88:89], off offset:1024
	global_load_dword v86, v[88:89], off offset:2048
	global_load_dword v87, v[88:89], off offset:3072
	v_addc_co_u32_e32 v91, vcc, 0, v131, vcc
	v_add_co_u32_e32 v94, vcc, 0x3000, v130
	s_nop 1
	v_addc_co_u32_e32 v95, vcc, 0, v131, vcc
	v_add_co_u32_e32 v98, vcc, 0x4000, v130
	global_load_dword v114, v[90:91], off
	global_load_dword v115, v[90:91], off offset:1024
	global_load_dword v88, v[90:91], off offset:2048
	global_load_dword v89, v[90:91], off offset:3072
	s_nop 0
	global_load_dword v90, v[94:95], off
	global_load_dword v91, v[94:95], off offset:1024
	global_load_dword v92, v[94:95], off offset:2048
	global_load_dword v93, v[94:95], off offset:3072
	v_addc_co_u32_e32 v99, vcc, 0, v131, vcc
	v_add_co_u32_e32 v110, vcc, 0x5000, v130
	s_nop 1
	v_addc_co_u32_e32 v111, vcc, 0, v131, vcc
	v_add_co_u32_e32 v118, vcc, 0x6000, v130
	global_load_dword v94, v[98:99], off
	global_load_dword v95, v[98:99], off offset:1024
	global_load_dword v96, v[98:99], off offset:2048
	global_load_dword v97, v[98:99], off offset:3072
	s_nop 0
	global_load_dword v98, v[110:111], off
	global_load_dword v99, v[110:111], off offset:1024
	global_load_dword v100, v[110:111], off offset:2048
	global_load_dword v117, v[110:111], off offset:3072
	v_addc_co_u32_e32 v119, vcc, 0, v131, vcc
	v_add_co_u32_e32 v124, vcc, 0x7000, v130
	s_nop 1
	v_addc_co_u32_e32 v125, vcc, 0, v131, vcc
	v_add_co_u32_e32 v126, vcc, 0x8000, v130
	global_load_dword v110, v[118:119], off
	global_load_dword v111, v[118:119], off offset:1024
	global_load_dword v112, v[118:119], off offset:2048
	global_load_dword v113, v[118:119], off offset:3072
	global_load_dword v116, v[124:125], off
	global_load_dword v121, v[124:125], off offset:1024
	global_load_dword v122, v[124:125], off offset:2048
	s_nop 0
	global_load_dword v124, v[124:125], off offset:3072
	v_addc_co_u32_e32 v127, vcc, 0, v131, vcc
	v_add_co_u32_e32 v128, vcc, 0x9000, v130
	s_nop 1
	v_addc_co_u32_e32 v129, vcc, 0, v131, vcc
	v_add_co_u32_e32 v132, vcc, 0xa000, v130
	global_load_dword v118, v[126:127], off
	global_load_dword v119, v[126:127], off offset:1024
	global_load_dword v120, v[126:127], off offset:2048
	global_load_dword v123, v[126:127], off offset:3072
	global_load_dword v125, v[128:129], off
	s_nop 0
	global_load_dword v126, v[128:129], off offset:1024
	global_load_dword v127, v[128:129], off offset:2048
	s_nop 0
	global_load_dword v129, v[128:129], off offset:3072
	v_addc_co_u32_e32 v133, vcc, 0, v131, vcc
	v_add_co_u32_e32 v180, vcc, 0xb000, v130
	s_nop 1
	v_addc_co_u32_e32 v181, vcc, 0, v131, vcc
	global_load_dword v128, v[132:133], off
	global_load_dword v130, v[132:133], off offset:1024
	global_load_dword v131, v[132:133], off offset:2048
	s_nop 0
	global_load_dword v132, v[132:133], off offset:3072
	s_nop 0
	global_load_dword v133, v[180:181], off
	global_load_dword v134, v[180:181], off offset:1024
	s_branch .LBB0_491
.LBB0_498:
	s_waitcnt vmcnt(3)
	v_mov_b32_e32 v0, v215
	v_mov_b32_e32 v25, s20
	v_readfirstlane_b32 s0, v0
	s_ashr_i32 s2, s0, 6
	s_lshl_b32 s0, s2, 14
	s_add_i32 s3, s0, 0
	s_add_u32 s10, s62, 0x600000
	v_and_b32_e32 v1, 63, v0
	s_addc_u32 s11, s63, 0
	s_add_u32 s16, s62, 0x800000
	v_or_b32_e32 v1, s2, v1
	s_addc_u32 s17, s63, 0
	v_cmp_eq_u32_e64 s[0:1], 0, v1
	v_bfe_u32 v18, v0, 5, 1
	v_lshlrev_b32_e32 v1, 2, v0
	s_add_u32 s12, s62, 0x1000000
	s_waitcnt vmcnt(0)
	v_and_b32_e32 v12, 0x7c, v1
	v_mul_u32_u24_e32 v1, 0x84, v18
	v_bfe_u32 v20, v0, 3, 3
	v_lshlrev_b32_e32 v0, 3, v0
	s_addc_u32 s13, s63, 0
	v_add3_u32 v19, s3, v12, v1
	v_and_b32_e32 v0, 56, v0
	v_mov_b32_e32 v1, 0
	v_mul_u32_u24_e32 v4, 0x84, v0
	v_lshlrev_b32_e32 v0, 1, v0
	v_lshlrev_b32_e32 v5, 2, v20
	v_mov_b32_e32 v13, v1
	s_cmp_lg_u64 s[68:69], 0
	v_lshl_add_u64 v[2:3], s[12:13], 0, v[0:1]
	v_add3_u32 v21, s3, v4, v5
	v_or_b32_e32 v22, 8, v20
	v_or_b32_e32 v23, 16, v20
	v_or_b32_e32 v24, 24, v20
	v_lshl_add_u64 v[4:5], s[16:17], 0, v[0:1]
	v_lshl_add_u64 v[6:7], s[10:11], 0, v[0:1]
	v_lshl_add_u64 v[8:9], s[72:73], 0, v[12:13]
	v_lshl_add_u64 v[10:11], s[70:71], 0, v[12:13]
	v_lshl_add_u64 v[12:13], s[30:31], 0, v[12:13]
	s_cselect_b64 s[8:9], -1, 0
	s_movk_i32 s3, 0x23f
	v_add_u32_e32 v26, 0x400, v19
	v_add_u32_e32 v27, 0x800, v19
	v_add_u32_e32 v28, 0xc00, v19
	v_add_u32_e32 v29, 0x1000, v19
	v_add_u32_e32 v30, 0x1400, v19
	v_add_u32_e32 v31, 0x1800, v19
	v_add_u32_e32 v32, 0x1c00, v19
	s_and_saveexec_b64 s[4:5], s[0:1]
	v_mov_b32_e32 v100, 1
	global_atomic_add v100, v1, v100, s[62:63] offset:384 sc0
	s_or_b64 exec, exec, s[4:5]
	s_branch .LBB0_501

.LBB0_501:
	s_and_saveexec_b64 s[4:5], s[0:1]
	s_cbranch_execz .LBB0_505
	s_waitcnt vmcnt(0)
	v_mov_b32_e32 v14, s20
	s_nop 0
	ds_write_b32 v14, v100
	v_mov_b32_e32 v100, 1
	global_atomic_add v100, v1, v100, s[62:63] offset:384 sc0

	.amdhsa_kernel _Z9hymba_fwd4Args
		.amdhsa_group_segment_fixed_size 0
		.amdhsa_private_segment_fixed_size 0
		.amdhsa_kernarg_size 456
		.amdhsa_user_sgpr_count 2
		.amdhsa_user_sgpr_dispatch_ptr 0
		.amdhsa_user_sgpr_queue_ptr 0
		.amdhsa_user_sgpr_kernarg_segment_ptr 1
		.amdhsa_user_sgpr_dispatch_id 0
		.amdhsa_user_sgpr_kernarg_preload_length 0
		.amdhsa_user_sgpr_kernarg_preload_offset 0
		.amdhsa_user_sgpr_private_segment_size 0
		.amdhsa_uses_dynamic_stack 0
		.amdhsa_enable_private_segment 0
		.amdhsa_system_sgpr_workgroup_id_x 1
		.amdhsa_system_sgpr_workgroup_id_y 0
		.amdhsa_system_sgpr_workgroup_id_z 0
		.amdhsa_system_sgpr_workgroup_info 0
		.amdhsa_system_vgpr_workitem_id 2
		.amdhsa_next_free_vgpr 255
		.amdhsa_next_free_sgpr 102
		.amdhsa_accum_offset 256
		.amdhsa_reserve_vcc 1
		.amdhsa_float_round_mode_32 0
		.amdhsa_float_round_mode_16_64 0
		.amdhsa_float_denorm_mode_32 3
		.amdhsa_float_denorm_mode_16_64 3
		.amdhsa_dx10_clamp 1
		.amdhsa_ieee_mode 1
		.amdhsa_fp16_overflow 0
		.amdhsa_tg_split 0
		.amdhsa_exception_fp_ieee_invalid_op 0
		.amdhsa_exception_fp_denorm_src 0
		.amdhsa_exception_fp_ieee_div_zero 0
		.amdhsa_exception_fp_ieee_overflow 0
		.amdhsa_exception_fp_ieee_underflow 0
		.amdhsa_exception_fp_ieee_inexact 0
		.amdhsa_exception_int_div_zero 0
	.end_amdhsa_kernel

amdhsa.kernels:
  - .agpr_count:     0
    .args:
      - .offset:         0
        .size:           200
        .value_kind:     by_value
      - .offset:         200
        .size:           4
        .value_kind:     hidden_block_count_x
      - .offset:         204
        .size:           4
        .value_kind:     hidden_block_count_y
      - .offset:         208
        .size:           4
        .value_kind:     hidden_block_count_z
      - .offset:         212
        .size:           2
        .value_kind:     hidden_group_size_x
      - .offset:         214
        .size:           2
        .value_kind:     hidden_group_size_y
      - .offset:         216
        .size:           2
        .value_kind:     hidden_group_size_z
      - .offset:         218
        .size:           2
        .value_kind:     hidden_remainder_x
      - .offset:         220
        .size:           2
        .value_kind:     hidden_remainder_y
      - .offset:         222
        .size:           2
        .value_kind:     hidden_remainder_z
      - .offset:         240
        .size:           8
        .value_kind:     hidden_global_offset_x
      - .offset:         248
        .size:           8
        .value_kind:     hidden_global_offset_y
      - .offset:         256
        .size:           8
        .value_kind:     hidden_global_offset_z
      - .offset:         264
        .size:           2
        .value_kind:     hidden_grid_dims
      - .offset:         288
        .size:           8
        .value_kind:     hidden_multigrid_sync_arg
      - .offset:         320
        .size:           4
        .value_kind:     hidden_dynamic_lds_size
    .group_segment_fixed_size: 0
    .kernarg_segment_align: 8
    .kernarg_segment_size: 456
    .language:       OpenCL C
    .language_version:
      - 2
      - 0
    .max_flat_workgroup_size: 512
    .name:           _Z9hymba_fwd4Args
    .private_segment_fixed_size: 0
    .sgpr_count:     108
    .sgpr_spill_count: 32
    .symbol:         _Z9hymba_fwd4Args.kd
    .uniform_work_group_size: 1
    .uses_dynamic_stack: false
    .vgpr_count:     255
    .vgpr_spill_count: 0
    .wavefront_size: 64
